# also conv-silu (phase 2) and glu-silu (phase 11): 1/x via single v_rcp_f32 instead of the IEEE division expansion
# speedup vs baseline: 1.0256x; 1.0019x over previous
.LBB0_658:
	s_or_b64 exec, exec, s[22:23]
	v_lshl_add_u64 v[20:21], s[12:13], 0, v[16:17]
	flat_load_dword v16, v[20:21]
	s_waitcnt vmcnt(0)
	v_lshlrev_b32_e32 v28, 16, v10
	s_waitcnt lgkmcnt(0)
	v_sub_f32_e32 v2, v2, v28
	v_cmp_lt_u32_e64 s[6:7], 63, v27
	v_cmp_lt_u32_e64 s[4:5], s31, v27
	v_fmac_f32_e32 v28, v16, v2
	s_and_saveexec_b64 s[0:1], s[6:7]
	s_xor_b64 s[22:23], exec, s[0:1]
	s_cbranch_execz .LBB0_662
	s_and_saveexec_b64 s[24:25], s[4:5]
	s_cbranch_execz .LBB0_661
	v_mul_f32_e32 v2, 0xbfb8aa3b, v28
	v_exp_f32_e32 v2, v2
	s_nop 0
	v_add_f32_e32 v2, 1.0, v2
	v_rcp_f32_e32 v28, v2

.LBB0_668:
	s_or_b64 exec, exec, s[22:23]
	v_lshlrev_b32_e32 v16, 2, v27
	v_lshl_add_u64 v[20:21], s[12:13], 0, v[16:17]
	v_add_co_u32_e32 v30, vcc, 0x3000, v20
	v_and_b32_e32 v2, 0xffff0000, v10
	s_nop 0
	v_addc_co_u32_e32 v31, vcc, 0, v21, vcc
	flat_load_dword v16, v[30:31] offset:4
	v_sub_f32_e32 v3, v3, v2
	s_waitcnt vmcnt(0) lgkmcnt(0)
	v_fmac_f32_e32 v2, v3, v16
	s_and_saveexec_b64 s[0:1], s[6:7]
	s_xor_b64 s[22:23], exec, s[0:1]
	s_cbranch_execz .LBB0_672
	s_and_saveexec_b64 s[24:25], s[4:5]
	s_cbranch_execz .LBB0_671
	v_mul_f32_e32 v2, 0xbfb8aa3b, v2
	v_exp_f32_e32 v2, v2
	s_nop 0
	v_add_f32_e32 v2, 1.0, v2
	v_rcp_f32_e32 v2, v2

.LBB0_678:
	s_or_b64 exec, exec, s[22:23]
	v_add_co_u32_e32 v30, vcc, 0x3000, v20
	v_lshlrev_b32_e32 v3, 16, v11
	s_nop 0
	v_addc_co_u32_e32 v31, vcc, 0, v21, vcc
	flat_load_dword v10, v[30:31] offset:8
	v_sub_f32_e32 v4, v4, v3
	s_waitcnt vmcnt(0) lgkmcnt(0)
	v_fmac_f32_e32 v3, v4, v10
	s_and_saveexec_b64 s[0:1], s[6:7]
	s_xor_b64 s[22:23], exec, s[0:1]
	s_cbranch_execz .LBB0_682
	s_and_saveexec_b64 s[24:25], s[4:5]
	s_cbranch_execz .LBB0_681
	v_mul_f32_e32 v3, 0xbfb8aa3b, v3
	v_exp_f32_e32 v3, v3
	s_nop 0
	v_add_f32_e32 v3, 1.0, v3
	v_rcp_f32_e32 v3, v3

.LBB0_688:
	s_or_b64 exec, exec, s[22:23]
	v_add_co_u32_e32 v30, vcc, 0x3000, v20
	v_and_b32_e32 v4, 0xffff0000, v11
	s_nop 0
	v_addc_co_u32_e32 v31, vcc, 0, v21, vcc
	flat_load_dword v10, v[30:31] offset:12
	v_sub_f32_e32 v5, v5, v4
	s_waitcnt vmcnt(0) lgkmcnt(0)
	v_fmac_f32_e32 v4, v5, v10
	s_and_saveexec_b64 s[0:1], s[6:7]
	s_xor_b64 s[22:23], exec, s[0:1]
	s_cbranch_execz .LBB0_692
	s_and_saveexec_b64 s[24:25], s[4:5]
	s_cbranch_execz .LBB0_691
	v_mul_f32_e32 v4, 0xbfb8aa3b, v4
	v_exp_f32_e32 v4, v4
	s_nop 0
	v_add_f32_e32 v4, 1.0, v4
	v_rcp_f32_e32 v4, v4

.LBB0_698:
	s_or_b64 exec, exec, s[22:23]
	v_add_co_u32_e32 v10, vcc, 0x3000, v20
	v_lshlrev_b32_e32 v5, 16, v12
	s_nop 0
	v_addc_co_u32_e32 v11, vcc, 0, v21, vcc
	flat_load_dword v10, v[10:11] offset:16
	v_sub_f32_e32 v6, v6, v5
	s_waitcnt vmcnt(0) lgkmcnt(0)
	v_fmac_f32_e32 v5, v6, v10
	s_and_saveexec_b64 s[0:1], s[6:7]
	s_xor_b64 s[22:23], exec, s[0:1]
	s_cbranch_execz .LBB0_702
	s_and_saveexec_b64 s[24:25], s[4:5]
	s_cbranch_execz .LBB0_701
	v_mul_f32_e32 v5, 0xbfb8aa3b, v5
	v_exp_f32_e32 v5, v5
	s_nop 0
	v_add_f32_e32 v5, 1.0, v5
	v_rcp_f32_e32 v5, v5

.LBB0_708:
	s_or_b64 exec, exec, s[22:23]
	v_add_co_u32_e32 v10, vcc, 0x3000, v20
	v_and_b32_e32 v6, 0xffff0000, v12
	s_nop 0
	v_addc_co_u32_e32 v11, vcc, 0, v21, vcc
	flat_load_dword v10, v[10:11] offset:20
	v_sub_f32_e32 v7, v7, v6
	s_waitcnt vmcnt(0) lgkmcnt(0)
	v_fmac_f32_e32 v6, v7, v10
	s_and_saveexec_b64 s[0:1], s[6:7]
	s_xor_b64 s[22:23], exec, s[0:1]
	s_cbranch_execz .LBB0_712
	s_and_saveexec_b64 s[24:25], s[4:5]
	s_cbranch_execz .LBB0_711
	v_mul_f32_e32 v6, 0xbfb8aa3b, v6
	v_exp_f32_e32 v6, v6
	s_nop 0
	v_add_f32_e32 v6, 1.0, v6
	v_rcp_f32_e32 v6, v6

.LBB0_718:
	s_or_b64 exec, exec, s[22:23]
	v_add_co_u32_e32 v10, vcc, 0x3000, v20
	v_lshlrev_b32_e32 v7, 16, v13
	s_nop 0
	v_addc_co_u32_e32 v11, vcc, 0, v21, vcc
	flat_load_dword v10, v[10:11] offset:24
	v_sub_f32_e32 v8, v8, v7
	s_waitcnt vmcnt(0) lgkmcnt(0)
	v_fmac_f32_e32 v7, v8, v10
	s_and_saveexec_b64 s[0:1], s[6:7]
	s_xor_b64 s[22:23], exec, s[0:1]
	s_cbranch_execz .LBB0_722
	s_and_saveexec_b64 s[24:25], s[4:5]
	s_cbranch_execz .LBB0_721
	v_mul_f32_e32 v7, 0xbfb8aa3b, v7
	v_exp_f32_e32 v7, v7
	s_nop 0
	v_add_f32_e32 v7, 1.0, v7
	v_rcp_f32_e32 v7, v7

.LBB0_728:
	s_or_b64 exec, exec, s[22:23]
	v_add_co_u32_e32 v10, vcc, 0x3000, v20
	v_and_b32_e32 v8, 0xffff0000, v13
	s_nop 0
	v_addc_co_u32_e32 v11, vcc, 0, v21, vcc
	flat_load_dword v10, v[10:11] offset:28
	v_sub_f32_e32 v9, v9, v8
	s_waitcnt vmcnt(0) lgkmcnt(0)
	v_fmac_f32_e32 v8, v9, v10
	s_and_saveexec_b64 s[0:1], s[6:7]
	s_xor_b64 s[6:7], exec, s[0:1]
	s_cbranch_execz .LBB0_732
	s_and_saveexec_b64 s[22:23], s[4:5]
	s_cbranch_execz .LBB0_731
	v_mul_f32_e32 v8, 0xbfb8aa3b, v8
	v_exp_f32_e32 v8, v8
	s_nop 0
	v_add_f32_e32 v8, 1.0, v8
	v_rcp_f32_e32 v8, v8

.LBB0_737:
	s_or_b64 exec, exec, s[16:17]
	s_mul_hi_i32 s0, s3, 0x2aaaaaab
	s_lshr_b32 s1, s0, 31
	s_ashr_i32 s3, s0, 6
	s_add_i32 s3, s3, s1
	s_mul_i32 s0, s3, 0x180
	s_add_i32 s1, 0, 0x20048
	v_cmp_gt_i32_e32 vcc, s0, v1
	s_add_i32 s0, 0, 0x20010
	v_mov_b32_e32 v2, s1
	v_mov_b32_e32 v6, s0
	ds_read2_b64 v[2:5], v2 offset1:1
	ds_read_b64 v[6:7], v6
	s_waitcnt lgkmcnt(0)
	v_readfirstlane_b32 s6, v2
	v_readfirstlane_b32 s7, v3
	v_readfirstlane_b32 s4, v4
	v_readfirstlane_b32 s5, v5
	v_readfirstlane_b32 s0, v6
	v_readfirstlane_b32 s1, v7
	s_and_saveexec_b64 s[12:13], vcc
	s_cbranch_execz .LBB0_763
	s_mov_b32 s14, 0xcc000
	v_cmp_gt_i32_e32 vcc, s14, v1
	s_and_b64 exec, exec, vcc
	s_cbranch_execz .LBB0_763
	s_mov_b32 s14, 0x2aaaaaab
	v_mul_hi_i32 v2, v1, s14
	v_lshrrev_b32_e32 v3, 31, v2
	v_ashrrev_i32_e32 v2, 6, v2
	v_add_u32_e32 v233, v2, v3
	v_mul_i32_i24_e32 v2, 0x180, v233
	v_sub_u32_e32 v88, v1, v2
	v_lshlrev_b32_e32 v146, 3, v88
	v_ashrrev_i32_e32 v147, 31, v146
	v_lshlrev_b64 v[34:35], 2, v[146:147]
	v_lshl_add_u64 v[26:27], s[6:7], 0, v[34:35]
	s_movk_i32 s6, 0x3000
	v_add_co_u32_e32 v18, vcc, s6, v26
	s_movk_i32 s6, 0x6000
	s_nop 0
	v_addc_co_u32_e32 v19, vcc, 0, v27, vcc
	s_nop 1
	v_add_co_u32_e32 v28, vcc, s6, v26
	s_mov_b32 s6, 0x9000
	s_nop 0
	v_addc_co_u32_e32 v29, vcc, 0, v27, vcc
	s_nop 1
	v_add_co_u32_e32 v36, vcc, s6, v26
	v_lshl_add_u64 v[42:43], s[4:5], 0, v[34:35]
	s_nop 0
	v_addc_co_u32_e32 v37, vcc, 0, v27, vcc
	flat_load_dwordx4 v[2:5], v[26:27]
	flat_load_dwordx4 v[6:9], v[26:27] offset:16
	flat_load_dwordx4 v[10:13], v[18:19]
	flat_load_dwordx4 v[14:17], v[18:19] offset:16
	s_nop 0
	flat_load_dwordx4 v[18:21], v[28:29]
	flat_load_dwordx4 v[22:25], v[28:29] offset:16
	s_nop 0
	flat_load_dwordx4 v[26:29], v[36:37]
	flat_load_dwordx4 v[30:33], v[36:37] offset:16
	s_nop 0
	flat_load_dwordx4 v[34:37], v[42:43]
	flat_load_dwordx4 v[38:41], v[42:43] offset:16
	s_mov_b32 s4, 0xc0000
	v_lshlrev_b32_e32 v89, 3, v233
	v_cmp_gt_i32_e32 vcc, s4, v1
	s_movk_i32 s4, 0x5200
	v_mov_b64_e32 v[42:43], s[10:11]
	v_mad_i64_i32 v[42:43], s[4:5], v89, s4, v[42:43]
	v_lshl_add_u64 v[42:43], v[146:147], 1, v[42:43]
	s_mov_b64 s[4:5], 0x1000
	v_lshl_add_u64 v[86:87], v[42:43], 0, s[4:5]
	v_mov_b32_e32 v42, 0
	v_mov_b32_e32 v44, v42
	v_mov_b32_e32 v45, v42
	v_cmp_ne_u32_sdwa s[4:5], v233, v42 src0_sel:BYTE_0 src1_sel:DWORD
	v_mov_b32_e32 v43, v42
	v_mov_b64_e32 v[52:53], v[44:45]
	v_mov_b64_e32 v[48:49], v[44:45]
	s_and_b64 s[4:5], vcc, s[4:5]
	v_mov_b64_e32 v[50:51], v[42:43]
	v_mov_b64_e32 v[46:47], v[42:43]
	s_and_saveexec_b64 s[6:7], s[4:5]
	s_cbranch_execz .LBB0_741
	v_add_co_u32_e32 v54, vcc, 0xffff1000, v86
	s_nop 1
	v_addc_co_u32_e32 v55, vcc, -1, v87, vcc
	s_nop 1
	v_add_co_u32_e32 v56, vcc, 0xffff6000, v86
	s_nop 1
	v_addc_co_u32_e32 v57, vcc, -1, v87, vcc
	global_load_dwordx4 v[46:49], v[54:55], off offset:-1536
	global_load_dwordx4 v[50:53], v[56:57], off offset:-1024

.LBB0_743:
	s_or_b64 exec, exec, s[6:7]
	v_add_co_u32_e32 v92, vcc, 0x23000, v86
	v_mov_b32_e32 v90, s0
	s_nop 0
	v_addc_co_u32_e32 v93, vcc, 0, v87, vcc
	s_nop 1
	v_add_co_u32_e32 v58, vcc, 0x1e000, v86
	v_mov_b32_e32 v91, s1
	s_nop 0
	v_addc_co_u32_e32 v59, vcc, 0, v87, vcc
	s_nop 1
	v_add_co_u32_e32 v60, vcc, 0x19000, v86
	v_lshl_add_u64 v[54:55], v[146:147], 1, s[46:47]
	s_nop 0
	v_addc_co_u32_e32 v61, vcc, 0, v87, vcc
	s_nop 1
	v_add_co_u32_e32 v62, vcc, 0x14000, v86
	s_mov_b64 s[0:1], 0x1bb00000
	s_nop 0
	v_addc_co_u32_e32 v63, vcc, 0, v87, vcc
	s_nop 1
	v_add_co_u32_e32 v64, vcc, 0xf000, v86
	v_mov_b32_e32 v151, 0
	s_nop 0
	v_addc_co_u32_e32 v65, vcc, 0, v87, vcc
	s_nop 1
	v_add_co_u32_e32 v94, vcc, 0xa000, v86
	v_mov_b32_e32 v150, v146
	s_nop 0
	v_addc_co_u32_e32 v95, vcc, 0, v87, vcc
	v_lshl_add_u64 v[148:149], v[54:55], 0, s[0:1]
	v_lshl_add_u64 v[54:55], v[150:151], 1, s[46:47]
	s_mov_b64 s[0:1], 0x3000000
	v_add_co_u32_e32 v96, vcc, 0x5000, v86
	v_lshl_add_u64 v[152:153], v[54:55], 0, s[0:1]
	global_load_dwordx4 v[70:73], v[58:59], off offset:3072
	global_load_dwordx4 v[54:57], v[60:61], off offset:2560
	global_load_dwordx4 v[74:77], v[62:63], off offset:2048
	s_nop 0
	global_load_dwordx4 v[58:61], v[64:65], off offset:1536
	v_addc_co_u32_e32 v97, vcc, 0, v87, vcc
	global_load_dwordx4 v[78:81], v[94:95], off offset:1024
	global_load_dwordx4 v[66:69], v[96:97], off offset:512
	global_load_dwordx4 v[82:85], v[92:93], off offset:3584
	global_load_dwordx4 v[62:65], v[86:87], off
	s_movk_i32 s4, 0x100
	s_waitcnt vmcnt(0) lgkmcnt(0)
	v_mov_b32_e32 v1, v25
	v_mov_b32_e32 v159, v25
	v_mov_b32_e32 v25, v17
	v_mov_b32_e32 v86, v23
	v_mov_b32_e32 v167, v23
	v_mov_b32_e32 v23, v15
	v_mov_b32_e32 v156, v32
	v_mov_b32_e32 v160, v8
	v_mov_b32_e32 v163, v17
	v_mov_b32_e32 v164, v30
	v_mov_b32_e32 v168, v6
	v_mov_b32_e32 v171, v15
	v_mov_b32_e32 v17, v8
	v_mov_b32_e32 v8, v25
	v_mov_b32_e32 v15, v6
	v_mov_b32_e32 v6, v23
	v_mov_b32_e32 v25, v32
	v_mov_b32_e32 v32, v1
	v_mov_b32_e32 v23, v30
	v_mov_b32_e32 v30, v86
	v_mov_b32_e32 v1, 0x400
	v_mov_b32_e32 v86, 0x800
	v_cmp_gt_i32_e64 s[4:5], s4, v88
	v_mov_b32_e32 v87, v21
	v_mov_b32_e32 v175, v21
	v_mov_b32_e32 v21, v13
	v_cndmask_b32_e64 v190, v1, v86, s[4:5]
	v_mov_b32_e32 v1, 0x1800
	v_mov_b32_e32 v86, 0x3000
	v_mov_b32_e32 v172, v28
	v_mov_b32_e32 v176, v4
	v_mov_b32_e32 v181, v13
	v_mov_b32_e32 v13, v4
	v_mov_b32_e32 v4, v21
	v_mov_b32_e32 v21, v28
	v_mov_b32_e32 v28, v87
	v_cndmask_b32_e64 v192, v1, v86, s[4:5]
	v_mov_b32_e32 v1, 0x2800
	v_mov_b32_e32 v87, 0x5000
	v_cndmask_b32_e64 v194, v1, v87, s[4:5]
	v_mov_b32_e32 v1, 0x6000
	v_lshl_add_u64 v[154:155], v[146:147], 2, v[90:91]
	v_mov_b32_e32 v90, v19
	v_mov_b32_e32 v185, v19
	v_mov_b32_e32 v19, v11
	v_cndmask_b32_e64 v196, v86, v1, s[4:5]
	v_mov_b32_e32 v1, 0x3800
	v_mov_b32_e32 v86, 0x7000
	s_movk_i32 s18, 0xf000
	v_mov_b32_e32 v157, v24
	v_mov_b32_e32 v158, v33
	v_mov_b32_e32 v161, v16
	v_mov_b32_e32 v162, v9
	v_mov_b32_e32 v165, v22
	v_mov_b32_e32 v166, v31
	v_mov_b32_e32 v169, v14
	v_mov_b32_e32 v170, v7
	v_mov_b32_e32 v173, v20
	v_mov_b32_e32 v174, v29
	v_mov_b32_e32 v177, v12
	v_mov_b32_e32 v180, v5
	v_mov_b32_e32 v182, v26
	v_mov_b32_e32 v183, v18
	v_mov_b32_e32 v184, v27
	v_mov_b32_e32 v186, v2
	v_mov_b32_e32 v187, v10
	v_mov_b32_e32 v188, v3
	v_mov_b32_e32 v189, v11
	v_mov_b32_e32 v11, v2
	v_mov_b32_e32 v2, v19
	v_mov_b32_e32 v19, v26
	v_mov_b32_e32 v26, v90
	s_movk_i32 s26, 0x800
	s_movk_i32 s27, 0x3000
	v_mov_b32_e32 v193, v151
	v_mov_b32_e32 v195, v151
	v_mov_b32_e32 v197, v151
	v_cndmask_b32_e64 v198, v1, v86, s[4:5]
	v_mov_b32_e32 v199, v151
	v_lshlrev_b32_e32 v200, 1, v190
	v_mov_b32_e32 v201, v151
	v_lshlrev_b32_e32 v202, 2, v190
	v_mov_b32_e32 v203, v151
	v_add_u32_e32 v1, 0xffffc000, v89
	s_lshl_b32 s28, s3, 4
	s_lshl_b32 s29, s3, 1
	s_lshl_b32 s30, s3, 3
	s_mov_b64 s[14:15], 0
	s_movk_i32 s31, 0x880
	s_movk_i32 s34, 0x5200
	s_mov_b64 s[16:17], 0x1000
	s_movk_i32 s35, 0x7ff
	s_mov_b32 s19, -1
	s_movk_i32 s36, 0x87f
	s_branch .LBB0_746
.LBB0_744:
	s_or_b64 exec, exec, s[6:7]
	v_add_u32_e32 v233, s3, v205
	v_ashrrev_i32_e32 v205, 31, v204
	v_lshlrev_b64 v[208:209], 12, v[204:205]
	v_lshlrev_b64 v[204:205], 11, v[204:205]
	v_lshl_add_u64 v[204:205], v[152:153], 0, v[204:205]
	v_lshl_add_u64 v[208:209], v[148:149], 0, v[208:209]
	v_lshl_add_u64 v[204:205], v[204:205], 0, s[18:19]
	v_cndmask_b32_e64 v205, v205, v209, s[4:5]
	v_cndmask_b32_e64 v204, v204, v208, s[4:5]
	v_pk_mul_f32 v[208:209], v[186:187], v[220:221]
	v_mov_b32_e32 v219, v142
	v_add_f32_e32 v135, v34, v208
	v_add_f32_e32 v135, v209, v135
	v_pk_mul_f32 v[208:209], v[188:189], v[138:139]
	v_mov_b32_e32 v143, v221
	v_add_f32_e32 v137, v35, v208
	v_add_f32_e32 v137, v209, v137
	v_pk_mul_f32 v[208:209], v[176:177], v[226:227]
	v_pk_mul_f32 v[142:143], v[10:11], v[142:143]
	v_add_f32_e32 v138, v36, v208
	v_add_f32_e32 v145, v209, v138
	v_pk_mul_f32 v[208:209], v[180:181], v[140:141]
	v_add_f32_e32 v143, v34, v143
	v_add_f32_e32 v138, v37, v208
	v_add_f32_e32 v140, v209, v138
	v_pk_mul_f32 v[208:209], v[168:169], v[222:223]
	v_add_f32_e32 v217, v142, v143
	v_add_f32_e32 v138, v38, v208
	v_add_f32_e32 v207, v209, v138
	v_pk_mul_f32 v[208:209], v[170:171], v[130:131]
	v_pk_mul_f32 v[224:225], v[162:163], v[132:133]
	v_add_f32_e32 v130, v39, v208
	v_add_f32_e32 v130, v209, v130
	v_pk_mul_f32 v[208:209], v[160:161], v[212:213]
	v_add_f32_e32 v132, v41, v224
	v_add_f32_e32 v138, v40, v208
	v_add_f32_e32 v212, v209, v138
	s_waitcnt vmcnt(15)
	v_lshlrev_b32_e32 v209, 16, v98
	v_mov_b32_e32 v218, v209
	v_pk_mul_f32 v[228:229], v[182:183], v[218:219]
	s_waitcnt vmcnt(14)
	v_lshlrev_b32_e32 v208, 16, v102
	v_add_f32_e32 v135, v229, v135
	v_add_f32_e32 v135, v228, v135
	v_mul_f32_e32 v138, 0xbfb8aa3b, v135
	v_exp_f32_e32 v138, v138
	v_add_f32_e32 v132, v225, v132
	v_add_u32_e32 v1, s28, v1
	v_add_f32_e32 v138, 1.0, v138
	v_pk_mul_f32 v[142:143], v[182:183], v[208:209]
	v_add_f32_e32 v143, v143, v217
	v_add_f32_e32 v142, v142, v143
	v_mul_f32_e32 v143, 0xbfb8aa3b, v142
	v_exp_f32_e32 v143, v143
	s_nop 0
	v_add_f32_e32 v217, 1.0, v143
	v_rcp_f32_e32 v211, v138
	s_nop 0
	v_mul_f32_e32 v135, v135, v211
	v_mov_b32_e32 v221, v210
	v_and_b32_e32 v143, 0xffff0000, v98
	v_mov_b32_e32 v220, v143
	v_pk_mul_f32 v[224:225], v[184:185], v[220:221]
	v_rcp_f32_e32 v138, v217
	s_nop 0
	v_mul_f32_e32 v234, v142, v138
	v_add_f32_e32 v137, v225, v137
	v_add_f32_e32 v137, v224, v137
	v_mul_f32_e32 v211, 0xbfb8aa3b, v137
	v_exp_f32_e32 v215, v211
	v_mov_b32_e32 v211, v139
	v_pk_mul_f32 v[138:139], v[2:3], v[210:211]
	v_and_b32_e32 v142, 0xffff0000, v102
	v_add_f32_e32 v210, 1.0, v215
	v_add_f32_e32 v139, v35, v139
	v_add_f32_e32 v217, v138, v139
	v_pk_mul_f32 v[138:139], v[184:185], v[142:143]
	v_add_f32_e32 v139, v139, v217
	v_add_f32_e32 v139, v138, v139
	v_mul_f32_e32 v138, 0xbfb8aa3b, v139
	v_exp_f32_e32 v138, v138
	s_nop 0
	v_add_f32_e32 v217, 1.0, v138
	v_rcp_f32_e32 v138, v210
	s_nop 0
	v_mul_f32_e32 v137, v137, v138
	v_cvt_pk_bf16_f32 v138, v135, v137
	v_lshlrev_b32_e32 v211, 16, v99
	v_mov_b32_e32 v224, v211
	v_mov_b32_e32 v225, v144
	v_pk_mul_f32 v[228:229], v[172:173], v[224:225]
	v_rcp_f32_e32 v135, v217
	s_nop 0
	v_mul_f32_e32 v235, v139, v135
	v_add_f32_e32 v137, v229, v145
	v_add_f32_e32 v137, v228, v137
	v_mul_f32_e32 v145, 0xbfb8aa3b, v137
	v_exp_f32_e32 v210, v145
	v_mov_b32_e32 v145, v227
	v_pk_mul_f32 v[144:145], v[12:13], v[144:145]
	v_mov_b32_e32 v227, v214
	v_add_f32_e32 v135, 1.0, v210
	v_add_f32_e32 v145, v36, v145
	v_add_f32_e32 v217, v144, v145
	v_lshlrev_b32_e32 v210, 16, v103
	v_pk_mul_f32 v[144:145], v[172:173], v[210:211]
	v_add_f32_e32 v145, v145, v217
	v_add_f32_e32 v144, v144, v145
	v_mul_f32_e32 v145, 0xbfb8aa3b, v144
	v_exp_f32_e32 v145, v145
	s_nop 0
	v_add_f32_e32 v217, 1.0, v145
	v_rcp_f32_e32 v139, v135
	s_nop 0
	v_mul_f32_e32 v135, v137, v139
	v_and_b32_e32 v145, 0xffff0000, v99
	v_mov_b32_e32 v226, v145
	v_pk_mul_f32 v[228:229], v[174:175], v[226:227]
	v_add_f32_e32 v139, v229, v140
	v_add_f32_e32 v139, v228, v139
	v_mul_f32_e32 v140, 0xbfb8aa3b, v139
	v_exp_f32_e32 v222, v140
	v_rcp_f32_e32 v137, v217
	s_nop 0
	v_mul_f32_e32 v236, v144, v137
	v_mov_b32_e32 v215, v141
	v_pk_mul_f32 v[140:141], v[4:5], v[214:215]
	v_add_f32_e32 v137, 1.0, v222
	v_add_f32_e32 v141, v37, v141
	v_add_f32_e32 v217, v140, v141
	v_and_b32_e32 v144, 0xffff0000, v103
	v_pk_mul_f32 v[140:141], v[174:175], v[144:145]
	v_add_f32_e32 v141, v141, v217
	v_add_f32_e32 v217, v140, v141
	v_mul_f32_e32 v140, 0xbfb8aa3b, v217
	v_exp_f32_e32 v140, v140
	s_nop 0
	v_add_f32_e32 v214, 1.0, v140
	v_rcp_f32_e32 v141, v137
	s_nop 0
	v_mul_f32_e32 v137, v139, v141
	v_cvt_pk_bf16_f32 v139, v135, v137
	v_lshlrev_b32_e32 v215, 16, v100
	v_mov_b32_e32 v228, v215
	v_mov_b32_e32 v229, v134
	v_pk_mul_f32 v[140:141], v[164:165], v[228:229]
	v_add_f32_e32 v137, v141, v207
	v_add_f32_e32 v137, v140, v137
	v_mul_f32_e32 v140, 0xbfb8aa3b, v137
	v_exp_f32_e32 v140, v140
	v_rcp_f32_e32 v135, v214
	s_nop 0
	v_mul_f32_e32 v237, v217, v135
	v_mov_b32_e32 v135, v223
	v_pk_mul_f32 v[134:135], v[14:15], v[134:135]
	v_add_f32_e32 v140, 1.0, v140
	v_add_f32_e32 v135, v38, v135
	v_add_f32_e32 v217, v134, v135
	v_lshlrev_b32_e32 v214, 16, v104
	v_pk_mul_f32 v[134:135], v[164:165], v[214:215]
	v_add_f32_e32 v135, v135, v217
	v_add_f32_e32 v134, v134, v135
	v_mul_f32_e32 v135, 0xbfb8aa3b, v134
	v_exp_f32_e32 v135, v135
	s_nop 0
	v_add_f32_e32 v217, 1.0, v135
	v_rcp_f32_e32 v141, v140
	s_nop 0
	v_mul_f32_e32 v137, v137, v141
	v_mov_b32_e32 v223, v216
	v_and_b32_e32 v135, 0xffff0000, v100
	v_mov_b32_e32 v222, v135
	v_pk_mul_f32 v[140:141], v[166:167], v[222:223]
	v_rcp_f32_e32 v207, v217
	s_nop 0
	v_mul_f32_e32 v238, v134, v207
	v_add_f32_e32 v130, v141, v130
	v_add_f32_e32 v140, v140, v130
	v_mul_f32_e32 v130, 0xbfb8aa3b, v140
	v_exp_f32_e32 v141, v130
	v_mov_b32_e32 v217, v131
	v_pk_mul_f32 v[130:131], v[6:7], v[216:217]
	v_and_b32_e32 v134, 0xffff0000, v104
	v_add_f32_e32 v141, 1.0, v141
	v_add_f32_e32 v131, v39, v131
	v_add_f32_e32 v217, v130, v131
	v_pk_mul_f32 v[130:131], v[166:167], v[134:135]
	v_add_f32_e32 v131, v131, v217
	v_add_f32_e32 v239, v130, v131
	v_mul_f32_e32 v130, 0xbfb8aa3b, v239
	v_exp_f32_e32 v130, v130
	s_nop 0
	v_add_f32_e32 v207, 1.0, v130
	v_rcp_f32_e32 v131, v141
	s_nop 0
	v_mul_f32_e32 v131, v140, v131
	v_cvt_pk_bf16_f32 v140, v137, v131
	v_lshlrev_b32_e32 v217, 16, v101
	v_mov_b32_e32 v230, v217
	v_mov_b32_e32 v231, v136
	v_pk_mul_f32 v[130:131], v[156:157], v[230:231]
	v_rcp_f32_e32 v137, v207
	s_nop 0
	v_mul_f32_e32 v239, v239, v137
	v_add_f32_e32 v131, v131, v212
	v_add_f32_e32 v141, v130, v131
	v_mul_f32_e32 v130, 0xbfb8aa3b, v141
	v_exp_f32_e32 v212, v130
	v_mov_b32_e32 v137, v213
	v_pk_mul_f32 v[130:131], v[16:17], v[136:137]
	v_lshlrev_b32_e32 v216, 16, v105
	v_add_f32_e32 v136, 1.0, v212
	v_add_f32_e32 v131, v40, v131
	v_add_f32_e32 v212, v130, v131
	v_pk_mul_f32 v[130:131], v[156:157], v[216:217]
	v_add_f32_e32 v131, v131, v212
	v_add_f32_e32 v241, v130, v131
	v_mul_f32_e32 v130, 0xbfb8aa3b, v241
	v_exp_f32_e32 v130, v130
	s_nop 0
	v_add_f32_e32 v242, 1.0, v130
	v_rcp_f32_e32 v131, v136
	s_nop 0
	v_mul_f32_e32 v141, v141, v131
	v_mov_b32_e32 v213, v206
	v_and_b32_e32 v137, 0xffff0000, v101
	v_mov_b32_e32 v212, v137
	v_pk_mul_f32 v[130:131], v[158:159], v[212:213]
	v_mov_b32_e32 v207, v133
	v_add_f32_e32 v131, v131, v132
	v_add_f32_e32 v132, v130, v131
	v_mul_f32_e32 v130, 0xbfb8aa3b, v132
	v_exp_f32_e32 v240, v130
	v_pk_mul_f32 v[130:131], v[8:9], v[206:207]
	v_rcp_f32_e32 v136, v242
	s_nop 0
	v_mul_f32_e32 v241, v241, v136
	v_add_f32_e32 v131, v41, v131
	v_add_f32_e32 v133, 1.0, v240
	v_add_f32_e32 v240, v130, v131
	v_and_b32_e32 v136, 0xffff0000, v105
	v_pk_mul_f32 v[130:131], v[158:159], v[136:137]
	v_add_f32_e32 v131, v131, v240
	v_add_f32_e32 v130, v130, v131
	v_mul_f32_e32 v131, 0xbfb8aa3b, v130
	v_exp_f32_e32 v131, v131
	v_rcp_f32_e32 v206, v133
	s_nop 0
	v_mul_f32_e32 v132, v132, v206
	v_cvt_pk_bf16_f32 v141, v141, v132
	v_add_f32_e32 v131, 1.0, v131
	global_store_dwordx4 v[204:205], v[138:141], off
	s_waitcnt vmcnt(13)
	v_lshlrev_b32_e32 v206, 16, v110
	v_rcp_f32_e32 v132, v131
	s_nop 0
	v_mul_f32_e32 v133, v130, v132
	v_cvt_pk_bf16_f32 v130, v234, v235
	v_cvt_pk_bf16_f32 v131, v236, v237
	v_lshl_add_u64 v[138:139], v[204:205], 0, v[150:151]
	v_cvt_pk_bf16_f32 v132, v238, v239
	v_cvt_pk_bf16_f32 v133, v241, v133
	global_store_dwordx4 v[138:139], v[130:133], off
	v_lshlrev_b32_e32 v207, 16, v106
	s_nop 0
	v_pk_mul_f32 v[130:131], v[10:11], v[218:219]
	s_nop 0
	v_add_f32_e32 v131, v34, v131
	v_add_f32_e32 v140, v130, v131
	v_pk_mul_f32 v[130:131], v[2:3], v[220:221]
	v_lshl_add_u64 v[220:221], v[138:139], 0, v[200:201]
	v_add_f32_e32 v131, v35, v131
	v_add_f32_e32 v141, v130, v131
	v_pk_mul_f32 v[130:131], v[12:13], v[224:225]
	s_nop 0
	v_add_f32_e32 v131, v36, v131
	v_add_f32_e32 v150, v130, v131
	v_pk_mul_f32 v[130:131], v[4:5], v[226:227]
	s_nop 0
	v_add_f32_e32 v131, v37, v131
	v_add_f32_e32 v218, v130, v131
	v_pk_mul_f32 v[130:131], v[14:15], v[228:229]
	s_nop 0
	v_add_f32_e32 v131, v38, v131
	v_add_f32_e32 v228, v130, v131
	v_pk_mul_f32 v[130:131], v[6:7], v[222:223]
	v_pk_mov_b32 v[222:223], v[206:207], v[208:209] op_sel:[1,0]
	v_add_f32_e32 v131, v39, v131
	v_pk_mul_f32 v[132:133], v[182:183], v[222:223]
	v_add_f32_e32 v229, v130, v131
	v_add_f32_e32 v133, v133, v140
	v_add_f32_e32 v132, v132, v133
	v_mul_f32_e32 v133, 0xbfb8aa3b, v132
	v_exp_f32_e32 v133, v133
	v_pk_mul_f32 v[130:131], v[16:17], v[230:231]
	v_add_f32_e32 v133, 1.0, v133
	v_add_f32_e32 v131, v40, v131
	v_add_f32_e32 v230, v130, v131
	v_pk_mul_f32 v[130:131], v[8:9], v[212:213]
	v_add_f32_e32 v131, v41, v131
	v_add_f32_e32 v234, v130, v131
	v_pk_mul_f32 v[130:131], v[10:11], v[208:209]
	v_add_f32_e32 v131, v34, v131
	v_add_f32_e32 v140, v130, v131
	v_pk_mul_f32 v[130:131], v[182:183], v[206:207]
	v_add_f32_e32 v131, v131, v140
	v_add_f32_e32 v140, v130, v131
	v_mul_f32_e32 v130, 0xbfb8aa3b, v140
	v_exp_f32_e32 v130, v130
	s_nop 0
	v_add_f32_e32 v212, 1.0, v130
	v_rcp_f32_e32 v131, v133
	s_nop 0
	v_mul_f32_e32 v132, v132, v131
	v_and_b32_e32 v139, 0xffff0000, v106
	v_and_b32_e32 v138, 0xffff0000, v110
	v_pk_mov_b32 v[208:209], v[138:139], v[142:143] op_sel:[1,0]
	v_pk_mul_f32 v[130:131], v[184:185], v[208:209]
	s_nop 0
	v_add_f32_e32 v131, v131, v141
	v_add_f32_e32 v141, v130, v131
	v_mul_f32_e32 v130, 0xbfb8aa3b, v141
	v_exp_f32_e32 v130, v130
	v_rcp_f32_e32 v131, v212
	s_nop 0
	v_mul_f32_e32 v235, v140, v131
	v_add_f32_e32 v133, 1.0, v130
	v_pk_mul_f32 v[130:131], v[2:3], v[142:143]
	v_add_f32_e32 v131, v35, v131
	v_add_f32_e32 v142, v130, v131
	v_pk_mul_f32 v[130:131], v[184:185], v[138:139]
	v_add_f32_e32 v131, v131, v142
	v_add_f32_e32 v131, v130, v131
	v_mul_f32_e32 v130, 0xbfb8aa3b, v131
	v_exp_f32_e32 v130, v130
	s_nop 0
	v_add_f32_e32 v219, 1.0, v130
	v_rcp_f32_e32 v130, v133
	s_nop 0
	v_mul_f32_e32 v130, v141, v130
	v_cvt_pk_bf16_f32 v130, v132, v130
	v_lshlrev_b32_e32 v143, 16, v107
	v_lshlrev_b32_e32 v142, 16, v111
	v_pk_mov_b32 v[224:225], v[142:143], v[210:211] op_sel:[1,0]
	s_nop 0
	v_pk_mul_f32 v[132:133], v[172:173], v[224:225]
	s_nop 0
	v_add_f32_e32 v133, v133, v150
	v_add_f32_e32 v150, v132, v133
	v_mul_f32_e32 v132, 0xbfb8aa3b, v150
	v_exp_f32_e32 v132, v132
	v_rcp_f32_e32 v133, v219
	s_nop 0
	v_mul_f32_e32 v236, v131, v133
	v_lshlrev_b32_e32 v219, 16, v108
	v_add_f32_e32 v131, 1.0, v132
	v_pk_mul_f32 v[132:133], v[12:13], v[210:211]
	v_add_f32_e32 v133, v36, v133
	v_add_f32_e32 v210, v132, v133
	v_pk_mul_f32 v[132:133], v[172:173], v[142:143]
	v_add_f32_e32 v133, v133, v210
	v_add_f32_e32 v210, v132, v133
	v_mul_f32_e32 v132, 0xbfb8aa3b, v210
	v_exp_f32_e32 v132, v132
	s_nop 0
	v_add_f32_e32 v211, 1.0, v132
	v_rcp_f32_e32 v133, v131
	s_nop 0
	v_mul_f32_e32 v131, v150, v133
	v_and_b32_e32 v141, 0xffff0000, v107
	v_and_b32_e32 v140, 0xffff0000, v111
	v_pk_mov_b32 v[226:227], v[140:141], v[144:145] op_sel:[1,0]
	v_pk_mul_f32 v[132:133], v[174:175], v[226:227]
	s_nop 0
	v_add_f32_e32 v133, v133, v218
	v_add_f32_e32 v218, v132, v133
	v_mul_f32_e32 v132, 0xbfb8aa3b, v218
	v_exp_f32_e32 v132, v132
	v_rcp_f32_e32 v133, v211
	s_nop 0
	v_mul_f32_e32 v150, v210, v133
	v_add_f32_e32 v210, 1.0, v132
	v_pk_mul_f32 v[132:133], v[4:5], v[144:145]
	v_add_f32_e32 v133, v37, v133
	v_add_f32_e32 v144, v132, v133
	v_pk_mul_f32 v[132:133], v[174:175], v[140:141]
	v_add_f32_e32 v133, v133, v144
	v_add_f32_e32 v231, v132, v133
	v_mul_f32_e32 v132, 0xbfb8aa3b, v231
	v_exp_f32_e32 v132, v132
	s_nop 0
	v_add_f32_e32 v211, 1.0, v132
	v_rcp_f32_e32 v133, v210
	s_nop 0
	v_mul_f32_e32 v133, v218, v133
	v_cvt_pk_bf16_f32 v131, v131, v133
	v_lshlrev_b32_e32 v218, 16, v112
	v_pk_mov_b32 v[144:145], v[218:219], v[214:215] op_sel:[1,0]
	v_pk_mul_f32 v[132:133], v[164:165], v[144:145]
	s_nop 0
	v_add_f32_e32 v133, v133, v228
	v_add_f32_e32 v213, v132, v133
	v_mul_f32_e32 v132, 0xbfb8aa3b, v213
	v_exp_f32_e32 v132, v132
	v_rcp_f32_e32 v133, v211
	s_nop 0
	v_mul_f32_e32 v237, v231, v133
	v_add_f32_e32 v210, 1.0, v132
	v_pk_mul_f32 v[132:133], v[14:15], v[214:215]
	v_add_f32_e32 v133, v38, v133
	v_add_f32_e32 v214, v132, v133
	v_pk_mul_f32 v[132:133], v[164:165], v[218:219]
	v_add_f32_e32 v133, v133, v214
	v_add_f32_e32 v231, v132, v133
	v_mul_f32_e32 v132, 0xbfb8aa3b, v231
	v_exp_f32_e32 v132, v132
	s_nop 0
	v_add_f32_e32 v238, 1.0, v132
	v_rcp_f32_e32 v133, v210
	s_nop 0
	v_mul_f32_e32 v212, v213, v133
	v_and_b32_e32 v211, 0xffff0000, v108
	v_and_b32_e32 v210, 0xffff0000, v112
	v_pk_mov_b32 v[214:215], v[210:211], v[134:135] op_sel:[1,0]
	v_pk_mul_f32 v[132:133], v[166:167], v[214:215]
	s_nop 0
	v_add_f32_e32 v133, v133, v229
	v_add_f32_e32 v229, v132, v133
	v_mul_f32_e32 v132, 0xbfb8aa3b, v229
	v_exp_f32_e32 v132, v132
	v_rcp_f32_e32 v133, v238
	s_nop 0
	v_mul_f32_e32 v238, v231, v133
	v_add_f32_e32 v213, 1.0, v132
	v_pk_mul_f32 v[132:133], v[6:7], v[134:135]
	v_add_f32_e32 v133, v39, v133
	v_add_f32_e32 v134, v132, v133
	v_pk_mul_f32 v[132:133], v[166:167], v[210:211]
	v_add_f32_e32 v133, v133, v134
	v_add_f32_e32 v133, v132, v133
	v_mul_f32_e32 v132, 0xbfb8aa3b, v133
	v_exp_f32_e32 v132, v132
	s_nop 0
	v_add_f32_e32 v240, 1.0, v132
	v_rcp_f32_e32 v132, v213
	s_nop 0
	v_mul_f32_e32 v132, v229, v132
	v_cvt_pk_bf16_f32 v132, v212, v132
	v_lshlrev_b32_e32 v135, 16, v109
	v_lshlrev_b32_e32 v134, 16, v113
	v_pk_mov_b32 v[228:229], v[134:135], v[216:217] op_sel:[1,0]
	s_nop 0
	v_pk_mul_f32 v[212:213], v[156:157], v[228:229]
	s_nop 0
	v_add_f32_e32 v213, v213, v230
	v_add_f32_e32 v230, v212, v213
	v_mul_f32_e32 v212, 0xbfb8aa3b, v230
	v_exp_f32_e32 v212, v212
	v_rcp_f32_e32 v213, v240
	s_nop 0
	v_mul_f32_e32 v239, v133, v213
	v_add_f32_e32 v133, 1.0, v212
	v_pk_mul_f32 v[212:213], v[16:17], v[216:217]
	v_add_f32_e32 v213, v40, v213
	v_add_f32_e32 v216, v212, v213
	v_pk_mul_f32 v[212:213], v[156:157], v[134:135]
	v_add_f32_e32 v213, v213, v216
	v_add_f32_e32 v242, v212, v213
	v_mul_f32_e32 v212, 0xbfb8aa3b, v242
	v_exp_f32_e32 v212, v212
	s_nop 0
	v_add_f32_e32 v243, 1.0, v212
	v_rcp_f32_e32 v213, v133
	s_nop 0
	v_mul_f32_e32 v133, v230, v213
	v_and_b32_e32 v213, 0xffff0000, v109
	v_and_b32_e32 v212, 0xffff0000, v113
	v_pk_mov_b32 v[216:217], v[212:213], v[136:137] op_sel:[1,0]
	v_pk_mul_f32 v[136:137], v[8:9], v[136:137]
	v_pk_mul_f32 v[230:231], v[158:159], v[216:217]
	v_add_f32_e32 v137, v41, v137
	v_add_f32_e32 v231, v231, v234
	v_add_f32_e32 v230, v230, v231
	v_mul_f32_e32 v231, 0xbfb8aa3b, v230
	v_exp_f32_e32 v231, v231
	v_rcp_f32_e32 v234, v243
	s_nop 0
	v_mul_f32_e32 v234, v242, v234
	v_add_f32_e32 v242, v136, v137
	v_add_f32_e32 v231, 1.0, v231
	v_pk_mul_f32 v[136:137], v[158:159], v[212:213]
	v_add_f32_e32 v137, v137, v242
	v_add_f32_e32 v136, v136, v137
	v_mul_f32_e32 v137, 0xbfb8aa3b, v136
	v_exp_f32_e32 v137, v137
	v_rcp_f32_e32 v240, v231
	s_nop 0
	v_mul_f32_e32 v230, v230, v240
	v_cvt_pk_bf16_f32 v133, v133, v230
	v_add_f32_e32 v137, 1.0, v137
	global_store_dwordx4 v[220:221], v[130:133], off
	s_nop 1
	v_rcp_f32_e32 v130, v137
	s_nop 0
	v_mul_f32_e32 v133, v136, v130
	v_cvt_pk_bf16_f32 v130, v235, v236
	v_cvt_pk_bf16_f32 v131, v150, v237
	v_lshl_add_u64 v[136:137], v[204:205], 0, v[192:193]
	v_cvt_pk_bf16_f32 v132, v238, v239
	v_cvt_pk_bf16_f32 v133, v234, v133
	global_store_dwordx4 v[136:137], v[130:133], off
	s_nop 1
	v_pk_mul_f32 v[130:131], v[10:11], v[222:223]
	s_nop 0
	v_add_f32_e32 v131, v34, v131
	v_add_f32_e32 v136, v130, v131
	v_pk_mul_f32 v[130:131], v[2:3], v[208:209]
	s_waitcnt vmcnt(15)
	v_lshlrev_b32_e32 v209, 16, v114
	v_add_f32_e32 v131, v35, v131
	v_add_f32_e32 v137, v130, v131
	v_pk_mul_f32 v[130:131], v[12:13], v[224:225]
	s_waitcnt vmcnt(14)
	v_lshlrev_b32_e32 v208, 16, v118
	v_add_f32_e32 v131, v36, v131
	v_add_f32_e32 v150, v130, v131
	v_pk_mul_f32 v[130:131], v[4:5], v[226:227]
	s_nop 0
	v_add_f32_e32 v131, v37, v131
	v_add_f32_e32 v226, v130, v131
	v_pk_mul_f32 v[130:131], v[14:15], v[144:145]
	s_nop 0
	v_add_f32_e32 v131, v38, v131
	v_add_f32_e32 v230, v130, v131
	v_pk_mul_f32 v[130:131], v[6:7], v[214:215]
	v_pk_mov_b32 v[214:215], v[208:209], v[206:207] op_sel:[1,0]
	v_add_f32_e32 v131, v39, v131
	v_pk_mul_f32 v[132:133], v[182:183], v[214:215]
	v_add_f32_e32 v231, v130, v131
	v_add_f32_e32 v133, v133, v136
	v_add_f32_e32 v132, v132, v133
	v_mul_f32_e32 v133, 0xbfb8aa3b, v132
	v_exp_f32_e32 v133, v133
	v_pk_mul_f32 v[130:131], v[16:17], v[228:229]
	v_add_f32_e32 v133, 1.0, v133
	v_add_f32_e32 v131, v40, v131
	v_add_f32_e32 v234, v130, v131
	v_pk_mul_f32 v[130:131], v[8:9], v[216:217]
	v_add_f32_e32 v131, v41, v131
	v_add_f32_e32 v235, v130, v131
	v_pk_mul_f32 v[130:131], v[10:11], v[206:207]
	v_add_f32_e32 v131, v34, v131
	v_add_f32_e32 v145, v130, v131
	v_pk_mul_f32 v[130:131], v[182:183], v[208:209]
	v_add_f32_e32 v131, v131, v145
	v_add_f32_e32 v145, v130, v131
	v_mul_f32_e32 v130, 0xbfb8aa3b, v145
	v_exp_f32_e32 v130, v130
	s_nop 0
	v_add_f32_e32 v136, 1.0, v130
	v_rcp_f32_e32 v131, v133
	s_nop 0
	v_mul_f32_e32 v132, v132, v131
	v_and_b32_e32 v207, 0xffff0000, v114
	v_and_b32_e32 v206, 0xffff0000, v118
	v_lshl_add_u64 v[216:217], v[220:221], 0, v[202:203]
	v_pk_mov_b32 v[220:221], v[206:207], v[138:139] op_sel:[1,0]
	v_pk_mul_f32 v[130:131], v[184:185], v[220:221]
	s_nop 0
	v_add_f32_e32 v131, v131, v137
	v_add_f32_e32 v137, v130, v131
	v_mul_f32_e32 v130, 0xbfb8aa3b, v137
	v_exp_f32_e32 v130, v130
	v_rcp_f32_e32 v131, v136
	s_nop 0
	v_mul_f32_e32 v236, v145, v131
	v_add_f32_e32 v133, 1.0, v130
	v_pk_mul_f32 v[130:131], v[2:3], v[138:139]
	v_add_f32_e32 v131, v35, v131
	v_add_f32_e32 v138, v130, v131
	v_pk_mul_f32 v[130:131], v[184:185], v[206:207]
	v_add_f32_e32 v131, v131, v138
	v_add_f32_e32 v131, v130, v131
	v_mul_f32_e32 v130, 0xbfb8aa3b, v131
	v_exp_f32_e32 v130, v130
	s_nop 0
	v_add_f32_e32 v138, 1.0, v130
	v_rcp_f32_e32 v130, v133
	s_nop 0
	v_mul_f32_e32 v130, v137, v130
	v_cvt_pk_bf16_f32 v130, v132, v130
	v_lshlrev_b32_e32 v145, 16, v115
	v_lshlrev_b32_e32 v144, 16, v119
	v_pk_mov_b32 v[222:223], v[144:145], v[142:143] op_sel:[1,0]
	v_pk_mul_f32 v[132:133], v[172:173], v[222:223]
	s_nop 0
	v_add_f32_e32 v133, v133, v150
	v_add_f32_e32 v139, v132, v133
	v_mul_f32_e32 v132, 0xbfb8aa3b, v139
	v_exp_f32_e32 v132, v132
	v_rcp_f32_e32 v133, v138
	s_nop 0
	v_mul_f32_e32 v150, v131, v133
	v_add_f32_e32 v131, 1.0, v132
	v_pk_mul_f32 v[132:133], v[12:13], v[142:143]
	v_add_f32_e32 v133, v36, v133
	v_add_f32_e32 v138, v132, v133
	v_pk_mul_f32 v[132:133], v[172:173], v[144:145]
	v_add_f32_e32 v133, v133, v138
	v_add_f32_e32 v138, v132, v133
	v_mul_f32_e32 v132, 0xbfb8aa3b, v138
	v_exp_f32_e32 v132, v132
	s_nop 0
	v_add_f32_e32 v136, 1.0, v132
	v_rcp_f32_e32 v133, v131
	s_nop 0
	v_mul_f32_e32 v131, v139, v133
	v_and_b32_e32 v143, 0xffff0000, v115
	v_and_b32_e32 v142, 0xffff0000, v119
	v_pk_mov_b32 v[224:225], v[142:143], v[140:141] op_sel:[1,0]
	v_pk_mul_f32 v[132:133], v[174:175], v[224:225]
	s_nop 0
	v_add_f32_e32 v133, v133, v226
	v_add_f32_e32 v226, v132, v133
	v_mul_f32_e32 v132, 0xbfb8aa3b, v226
	v_exp_f32_e32 v132, v132
	v_rcp_f32_e32 v133, v136
	s_nop 0
	v_mul_f32_e32 v237, v138, v133
	v_add_f32_e32 v136, 1.0, v132
	v_pk_mul_f32 v[132:133], v[4:5], v[140:141]
	v_add_f32_e32 v133, v37, v133
	v_add_f32_e32 v139, v132, v133
	v_pk_mul_f32 v[132:133], v[174:175], v[142:143]
	v_add_f32_e32 v133, v133, v139
	v_add_f32_e32 v139, v132, v133
	v_mul_f32_e32 v132, 0xbfb8aa3b, v139
	v_exp_f32_e32 v132, v132
	s_nop 0
	v_add_f32_e32 v137, 1.0, v132
	v_rcp_f32_e32 v133, v136
	s_nop 0
	v_mul_f32_e32 v133, v226, v133
	v_cvt_pk_bf16_f32 v131, v131, v133
	v_lshlrev_b32_e32 v141, 16, v116
	v_lshlrev_b32_e32 v140, 16, v120
	v_pk_mov_b32 v[226:227], v[140:141], v[218:219] op_sel:[1,0]
	v_pk_mul_f32 v[132:133], v[164:165], v[226:227]
	s_nop 0
	v_add_f32_e32 v133, v133, v230
	v_add_f32_e32 v229, v132, v133
	v_mul_f32_e32 v132, 0xbfb8aa3b, v229
	v_exp_f32_e32 v132, v132
	v_rcp_f32_e32 v133, v137
	s_nop 0
	v_mul_f32_e32 v238, v139, v133
	v_add_f32_e32 v136, 1.0, v132
	v_pk_mul_f32 v[132:133], v[14:15], v[218:219]
	v_add_f32_e32 v133, v38, v133
	v_add_f32_e32 v139, v132, v133
	v_pk_mul_f32 v[132:133], v[164:165], v[140:141]
	v_add_f32_e32 v133, v133, v139
	v_add_f32_e32 v228, v132, v133
	v_mul_f32_e32 v132, 0xbfb8aa3b, v228
	v_exp_f32_e32 v132, v132
	s_nop 0
	v_add_f32_e32 v137, 1.0, v132
	v_rcp_f32_e32 v133, v136
	s_nop 0
	v_mul_f32_e32 v136, v229, v133
	v_and_b32_e32 v139, 0xffff0000, v116
	v_and_b32_e32 v138, 0xffff0000, v120
	v_pk_mov_b32 v[218:219], v[138:139], v[210:211] op_sel:[1,0]
	v_pk_mul_f32 v[132:133], v[166:167], v[218:219]
	s_nop 0
	v_add_f32_e32 v133, v133, v231
	v_add_f32_e32 v231, v132, v133
	v_mul_f32_e32 v132, 0xbfb8aa3b, v231
	v_exp_f32_e32 v132, v132
	v_rcp_f32_e32 v133, v137
	s_nop 0
	v_mul_f32_e32 v239, v228, v133
	v_add_f32_e32 v137, 1.0, v132
	v_pk_mul_f32 v[132:133], v[6:7], v[210:211]
	v_add_f32_e32 v133, v39, v133
	v_add_f32_e32 v210, v132, v133
	v_pk_mul_f32 v[132:133], v[166:167], v[138:139]
	v_add_f32_e32 v133, v133, v210
	v_add_f32_e32 v133, v132, v133
	v_mul_f32_e32 v132, 0xbfb8aa3b, v133
	v_exp_f32_e32 v132, v132
	s_nop 0
	v_add_f32_e32 v240, 1.0, v132
	v_rcp_f32_e32 v132, v137
	s_nop 0
	v_mul_f32_e32 v132, v231, v132
	v_cvt_pk_bf16_f32 v132, v136, v132
	v_lshlrev_b32_e32 v137, 16, v117
	v_lshlrev_b32_e32 v136, 16, v121
	v_pk_mov_b32 v[210:211], v[136:137], v[134:135] op_sel:[1,0]
	v_pk_mul_f32 v[228:229], v[156:157], v[210:211]
	v_pk_mul_f32 v[134:135], v[16:17], v[134:135]
	v_add_f32_e32 v229, v229, v234
	v_add_f32_e32 v228, v228, v229
	v_mul_f32_e32 v229, 0xbfb8aa3b, v228
	v_exp_f32_e32 v229, v229
	v_rcp_f32_e32 v230, v240
	s_nop 0
	v_mul_f32_e32 v234, v133, v230
	v_add_f32_e32 v135, v40, v135
	v_add_f32_e32 v231, v134, v135
	v_add_f32_e32 v133, 1.0, v229
	v_pk_mul_f32 v[134:135], v[156:157], v[136:137]
	v_add_f32_e32 v135, v135, v231
	v_add_f32_e32 v242, v134, v135
	v_mul_f32_e32 v134, 0xbfb8aa3b, v242
	v_exp_f32_e32 v134, v134
	s_nop 0
	v_add_f32_e32 v240, 1.0, v134
	v_rcp_f32_e32 v135, v133
	s_nop 0
	v_mul_f32_e32 v133, v228, v135
	v_and_b32_e32 v135, 0xffff0000, v117
	v_and_b32_e32 v134, 0xffff0000, v121
	v_pk_mov_b32 v[228:229], v[134:135], v[212:213] op_sel:[1,0]
	v_pk_mul_f32 v[212:213], v[8:9], v[212:213]
	v_pk_mul_f32 v[230:231], v[158:159], v[228:229]
	v_add_f32_e32 v213, v41, v213
	v_add_f32_e32 v231, v231, v235
	v_add_f32_e32 v230, v230, v231
	v_mul_f32_e32 v231, 0xbfb8aa3b, v230
	v_exp_f32_e32 v231, v231
	v_rcp_f32_e32 v235, v240
	s_nop 0
	v_mul_f32_e32 v235, v242, v235
	v_add_f32_e32 v242, v212, v213
	v_add_f32_e32 v231, 1.0, v231
	v_pk_mul_f32 v[212:213], v[158:159], v[134:135]
	v_add_f32_e32 v213, v213, v242
	v_add_f32_e32 v212, v212, v213
	v_mul_f32_e32 v213, 0xbfb8aa3b, v212
	v_exp_f32_e32 v213, v213
	v_rcp_f32_e32 v240, v231
	s_nop 0
	v_mul_f32_e32 v230, v230, v240
	v_cvt_pk_bf16_f32 v133, v133, v230
	v_add_f32_e32 v213, 1.0, v213
	global_store_dwordx4 v[216:217], v[130:133], off
	s_nop 1
	v_rcp_f32_e32 v130, v213
	s_nop 0
	v_mul_f32_e32 v133, v212, v130
	v_cvt_pk_bf16_f32 v130, v236, v150
	v_cvt_pk_bf16_f32 v131, v237, v238
	v_lshl_add_u64 v[212:213], v[204:205], 0, v[194:195]
	v_cvt_pk_bf16_f32 v132, v239, v234
	v_cvt_pk_bf16_f32 v133, v235, v133
	global_store_dwordx4 v[212:213], v[130:133], off
	s_nop 1
	v_pk_mul_f32 v[130:131], v[10:11], v[214:215]
	s_waitcnt vmcnt(15)
	v_lshlrev_b32_e32 v133, 16, v122
	v_add_f32_e32 v131, v34, v131
	v_add_f32_e32 v150, v130, v131
	v_pk_mul_f32 v[130:131], v[2:3], v[220:221]
	s_waitcnt vmcnt(14)
	v_lshlrev_b32_e32 v132, 16, v126
	v_add_f32_e32 v131, v35, v131
	v_add_f32_e32 v212, v130, v131
	v_pk_mul_f32 v[130:131], v[12:13], v[222:223]
	s_nop 0
	v_add_f32_e32 v131, v36, v131
	v_add_f32_e32 v213, v130, v131
	v_pk_mul_f32 v[130:131], v[4:5], v[224:225]
	s_nop 0
	v_add_f32_e32 v131, v37, v131
	v_add_f32_e32 v214, v130, v131
	v_pk_mul_f32 v[130:131], v[14:15], v[226:227]
	s_nop 0
	v_add_f32_e32 v131, v38, v131
	v_add_f32_e32 v215, v130, v131
	v_pk_mul_f32 v[130:131], v[6:7], v[218:219]
	s_nop 0
	v_add_f32_e32 v131, v39, v131
	v_add_f32_e32 v216, v130, v131
	v_pk_mul_f32 v[130:131], v[16:17], v[210:211]
	v_pk_mov_b32 v[210:211], v[132:133], v[208:209] op_sel:[1,0]
	v_add_f32_e32 v131, v40, v131
	v_pk_mul_f32 v[210:211], v[182:183], v[210:211]
	v_add_f32_e32 v217, v130, v131
	v_add_f32_e32 v150, v211, v150
	v_add_f32_e32 v150, v210, v150
	v_mul_f32_e32 v210, 0xbfb8aa3b, v150
	v_exp_f32_e32 v218, v210
	v_pk_mul_f32 v[130:131], v[8:9], v[228:229]
	v_lshl_add_u64 v[210:211], v[204:205], 0, v[196:197]
	v_add_f32_e32 v131, v41, v131
	v_add_f32_e32 v218, 1.0, v218
	v_add_f32_e32 v219, v130, v131
	v_pk_mul_f32 v[130:131], v[10:11], v[208:209]
	v_add_f32_e32 v131, v34, v131
	v_add_f32_e32 v208, v130, v131
	v_pk_mul_f32 v[130:131], v[182:183], v[132:133]
	v_add_f32_e32 v131, v131, v208
	v_add_f32_e32 v208, v130, v131
	v_mul_f32_e32 v130, 0xbfb8aa3b, v208
	v_exp_f32_e32 v130, v130
	s_nop 0
	v_add_f32_e32 v209, 1.0, v130
	v_rcp_f32_e32 v131, v218
	s_nop 0
	v_mul_f32_e32 v150, v150, v131
	v_and_b32_e32 v131, 0xffff0000, v122
	v_and_b32_e32 v130, 0xffff0000, v126
	v_pk_mov_b32 v[132:133], v[130:131], v[206:207] op_sel:[1,0]
	v_pk_mul_f32 v[130:131], v[184:185], v[130:131]
	v_pk_mul_f32 v[132:133], v[184:185], v[132:133]
	s_nop 0
	v_add_f32_e32 v133, v133, v212
	v_add_f32_e32 v212, v132, v133
	v_mul_f32_e32 v132, 0xbfb8aa3b, v212
	v_exp_f32_e32 v132, v132
	v_rcp_f32_e32 v133, v209
	s_nop 0
	v_mul_f32_e32 v208, v208, v133
	v_add_f32_e32 v209, 1.0, v132
	v_pk_mul_f32 v[132:133], v[2:3], v[206:207]
	v_add_f32_e32 v133, v35, v133
	v_add_f32_e32 v132, v132, v133
	v_add_f32_e32 v131, v131, v132
	v_add_f32_e32 v131, v130, v131
	v_mul_f32_e32 v130, 0xbfb8aa3b, v131
	v_exp_f32_e32 v130, v130
	s_nop 0
	v_add_f32_e32 v218, 1.0, v130
	v_rcp_f32_e32 v130, v209
	s_nop 0
	v_mul_f32_e32 v130, v212, v130
	v_cvt_pk_bf16_f32 v130, v150, v130
	v_lshlrev_b32_e32 v133, 16, v123
	v_lshlrev_b32_e32 v132, 16, v127
	v_pk_mov_b32 v[206:207], v[132:133], v[144:145] op_sel:[1,0]
	v_pk_mul_f32 v[206:207], v[172:173], v[206:207]
	v_rcp_f32_e32 v150, v218
	s_nop 0
	v_mul_f32_e32 v150, v131, v150
	v_add_f32_e32 v207, v207, v213
	v_add_f32_e32 v206, v206, v207
	v_mul_f32_e32 v207, 0xbfb8aa3b, v206
	v_exp_f32_e32 v207, v207
	v_pk_mul_f32 v[144:145], v[12:13], v[144:145]
	v_pk_mul_f32 v[132:133], v[172:173], v[132:133]
	v_add_f32_e32 v145, v36, v145
	v_add_f32_e32 v131, 1.0, v207
	v_add_f32_e32 v144, v144, v145
	v_add_f32_e32 v133, v133, v144
	v_add_f32_e32 v213, v132, v133
	v_mul_f32_e32 v132, 0xbfb8aa3b, v213
	v_exp_f32_e32 v132, v132
	s_nop 0
	v_add_f32_e32 v207, 1.0, v132
	v_rcp_f32_e32 v133, v131
	s_nop 0
	v_mul_f32_e32 v131, v206, v133
	v_and_b32_e32 v133, 0xffff0000, v123
	v_and_b32_e32 v132, 0xffff0000, v127
	v_pk_mov_b32 v[144:145], v[132:133], v[142:143] op_sel:[1,0]
	v_pk_mul_f32 v[144:145], v[174:175], v[144:145]
	v_rcp_f32_e32 v206, v207
	s_nop 0
	v_mul_f32_e32 v206, v213, v206
	v_add_f32_e32 v145, v145, v214
	v_add_f32_e32 v144, v144, v145
	v_mul_f32_e32 v145, 0xbfb8aa3b, v144
	v_exp_f32_e32 v145, v145
	v_pk_mul_f32 v[142:143], v[4:5], v[142:143]
	v_pk_mul_f32 v[132:133], v[174:175], v[132:133]
	v_add_f32_e32 v143, v37, v143
	v_add_f32_e32 v145, 1.0, v145
	v_add_f32_e32 v142, v142, v143
	v_add_f32_e32 v133, v133, v142
	v_add_f32_e32 v213, v132, v133
	v_mul_f32_e32 v132, 0xbfb8aa3b, v213
	v_exp_f32_e32 v132, v132
	s_nop 0
	v_add_f32_e32 v207, 1.0, v132
	v_rcp_f32_e32 v133, v145
	s_nop 0
	v_mul_f32_e32 v133, v144, v133
	v_cvt_pk_bf16_f32 v131, v131, v133
	v_lshlrev_b32_e32 v133, 16, v124
	v_lshlrev_b32_e32 v132, 16, v128
	v_pk_mov_b32 v[142:143], v[132:133], v[140:141] op_sel:[1,0]
	v_pk_mul_f32 v[142:143], v[164:165], v[142:143]
	v_pk_mul_f32 v[140:141], v[14:15], v[140:141]
	v_add_f32_e32 v143, v143, v215
	v_add_f32_e32 v142, v142, v143
	v_mul_f32_e32 v143, 0xbfb8aa3b, v142
	v_exp_f32_e32 v143, v143
	v_rcp_f32_e32 v144, v207
	s_nop 0
	v_mul_f32_e32 v144, v213, v144
	v_add_f32_e32 v141, v38, v141
	v_add_f32_e32 v140, v140, v141
	v_add_f32_e32 v143, 1.0, v143
	v_pk_mul_f32 v[132:133], v[164:165], v[132:133]
	v_add_f32_e32 v133, v133, v140
	v_add_f32_e32 v212, v132, v133
	v_mul_f32_e32 v132, 0xbfb8aa3b, v212
	v_exp_f32_e32 v132, v132
	s_nop 0
	v_add_f32_e32 v145, 1.0, v132
	v_rcp_f32_e32 v133, v143
	s_nop 0
	v_mul_f32_e32 v142, v142, v133
	v_and_b32_e32 v133, 0xffff0000, v124
	v_and_b32_e32 v132, 0xffff0000, v128
	v_pk_mov_b32 v[140:141], v[132:133], v[138:139] op_sel:[1,0]
	v_pk_mul_f32 v[140:141], v[166:167], v[140:141]
	v_rcp_f32_e32 v143, v145
	s_nop 0
	v_mul_f32_e32 v143, v212, v143
	v_add_f32_e32 v141, v141, v216
	v_add_f32_e32 v140, v140, v141
	v_mul_f32_e32 v141, 0xbfb8aa3b, v140
	v_exp_f32_e32 v141, v141
	v_pk_mul_f32 v[138:139], v[6:7], v[138:139]
	v_pk_mul_f32 v[132:133], v[166:167], v[132:133]
	v_add_f32_e32 v139, v39, v139
	v_add_f32_e32 v141, 1.0, v141
	v_add_f32_e32 v138, v138, v139
	v_add_f32_e32 v133, v133, v138
	v_add_f32_e32 v133, v132, v133
	v_mul_f32_e32 v132, 0xbfb8aa3b, v133
	v_exp_f32_e32 v132, v132
	s_nop 0
	v_add_f32_e32 v145, 1.0, v132
	v_rcp_f32_e32 v132, v141
	s_nop 0
	v_mul_f32_e32 v132, v140, v132
	v_cvt_pk_bf16_f32 v132, v142, v132
	v_lshlrev_b32_e32 v139, 16, v125
	v_lshlrev_b32_e32 v138, 16, v129
	v_pk_mov_b32 v[140:141], v[138:139], v[136:137] op_sel:[1,0]
	v_pk_mul_f32 v[140:141], v[156:157], v[140:141]
	v_rcp_f32_e32 v142, v145
	s_nop 0
	v_mul_f32_e32 v142, v133, v142
	v_add_f32_e32 v141, v141, v217
	v_add_f32_e32 v140, v140, v141
	v_mul_f32_e32 v141, 0xbfb8aa3b, v140
	v_exp_f32_e32 v141, v141
	v_pk_mul_f32 v[136:137], v[16:17], v[136:137]
	v_add_f32_e32 v133, 1.0, v141
	v_add_f32_e32 v137, v40, v137
	v_add_f32_e32 v207, v136, v137
	v_pk_mul_f32 v[136:137], v[156:157], v[138:139]
	v_add_f32_e32 v137, v137, v207
	v_add_f32_e32 v207, v136, v137
	v_mul_f32_e32 v136, 0xbfb8aa3b, v207
	v_exp_f32_e32 v136, v136
	s_nop 0
	v_add_f32_e32 v141, 1.0, v136
	v_rcp_f32_e32 v137, v133
	s_nop 0
	v_mul_f32_e32 v133, v140, v137
	v_and_b32_e32 v137, 0xffff0000, v125
	v_and_b32_e32 v136, 0xffff0000, v129
	v_pk_mov_b32 v[138:139], v[136:137], v[134:135] op_sel:[1,0]
	v_pk_mul_f32 v[138:139], v[158:159], v[138:139]
	v_rcp_f32_e32 v140, v141
	s_nop 0
	v_mul_f32_e32 v140, v207, v140
	v_add_f32_e32 v139, v139, v219
	v_add_f32_e32 v138, v138, v139
	v_mul_f32_e32 v139, 0xbfb8aa3b, v138
	v_exp_f32_e32 v139, v139
	v_pk_mul_f32 v[134:135], v[8:9], v[134:135]
	v_add_f32_e32 v139, 1.0, v139
	v_add_f32_e32 v135, v41, v135
	v_add_f32_e32 v207, v134, v135
	v_pk_mul_f32 v[134:135], v[158:159], v[136:137]
	v_add_f32_e32 v135, v135, v207
	v_add_f32_e32 v134, v134, v135
	v_mul_f32_e32 v135, 0xbfb8aa3b, v134
	v_exp_f32_e32 v135, v135
	v_rcp_f32_e32 v136, v139
	s_nop 0
	v_mul_f32_e32 v136, v138, v136
	v_cvt_pk_bf16_f32 v133, v133, v136
	v_add_f32_e32 v135, 1.0, v135
	global_store_dwordx4 v[210:211], v[130:133], off
	s_nop 1
	v_cmp_lt_i32_e32 vcc, s36, v233
	v_rcp_f32_e32 v130, v135
	s_nop 0
	v_mul_f32_e32 v133, v134, v130
	v_lshl_add_u64 v[134:135], v[204:205], 0, v[198:199]
	s_orn2_b64 s[22:23], vcc, exec
	v_cvt_pk_bf16_f32 v130, v208, v150
	v_cvt_pk_bf16_f32 v131, v206, v144
	v_cvt_pk_bf16_f32 v132, v143, v142
	v_cvt_pk_bf16_f32 v133, v140, v133
	global_store_dwordx4 v[134:135], v[130:133], off

.LBB0_746:
	v_add_u32_e32 v205, s3, v233
	v_add_u32_e32 v234, s30, v1
	v_cmp_gt_i32_e64 s[6:7], s31, v205
	v_add_u32_e32 v204, 0x4000, v234
	s_and_saveexec_b64 s[20:21], s[6:7]
	s_cbranch_execz .LBB0_752
	s_waitcnt vmcnt(16)
	v_mov_b64_e32 v[86:87], s[10:11]
	v_mad_i64_i32 v[86:87], s[0:1], v204, s34, v[86:87]
	v_cmp_gt_i32_e32 vcc, s26, v205
	v_lshl_add_u64 v[86:87], v[146:147], 1, v[86:87]
	v_cmp_ne_u32_sdwa s[0:1], v205, v151 src0_sel:BYTE_0 src1_sel:DWORD
	s_waitcnt vmcnt(9)
	v_lshl_add_u64 v[122:123], v[86:87], 0, s[16:17]
	v_mov_b32_e32 v86, 0
	s_and_b64 s[22:23], vcc, s[0:1]
	v_mov_b32_e32 v94, 0
	v_mov_b32_e32 v95, 0
	v_mov_b32_e32 v96, 0
	v_mov_b32_e32 v97, 0
	v_mov_b32_e32 v90, 0
	v_mov_b32_e32 v91, 0
	v_mov_b32_e32 v92, 0
	v_mov_b32_e32 v93, 0
	s_and_saveexec_b64 s[24:25], s[22:23]
	s_cbranch_execz .LBB0_749
	v_add_co_u32_e32 v88, vcc, 0xffff1000, v122
	s_nop 1
	v_addc_co_u32_e32 v89, vcc, -1, v123, vcc
	s_nop 1
	v_add_co_u32_e32 v94, vcc, 0xffff6000, v122
	s_nop 1
	v_addc_co_u32_e32 v95, vcc, -1, v123, vcc
	global_load_dwordx4 v[90:93], v[88:89], off offset:-1536
	s_nop 0
	global_load_dwordx4 v[94:97], v[94:95], off offset:-1024

.LBB0_751:
	s_or_b64 exec, exec, s[24:25]
	v_add_co_u32_e32 v102, vcc, 0x5000, v122
	s_nop 1
	v_addc_co_u32_e32 v103, vcc, 0, v123, vcc
	s_nop 1
	v_add_co_u32_e32 v106, vcc, 0xa000, v122
	global_load_dwordx4 v[98:101], v[122:123], off
	s_nop 0
	global_load_dwordx4 v[102:105], v[102:103], off offset:512
	v_addc_co_u32_e32 v107, vcc, 0, v123, vcc
	s_nop 1
	v_add_co_u32_e32 v110, vcc, 0xf000, v122
	s_nop 1
	v_addc_co_u32_e32 v111, vcc, 0, v123, vcc
	s_nop 1
	v_add_co_u32_e32 v114, vcc, 0x14000, v122
	global_load_dwordx4 v[106:109], v[106:107], off offset:1024
	s_nop 0
	global_load_dwordx4 v[110:113], v[110:111], off offset:1536
	v_addc_co_u32_e32 v115, vcc, 0, v123, vcc
	s_nop 1
	v_add_co_u32_e32 v118, vcc, 0x19000, v122
	s_nop 1
	v_addc_co_u32_e32 v119, vcc, 0, v123, vcc
	s_nop 1
	v_add_co_u32_e32 v124, vcc, 0x1e000, v122
	global_load_dwordx4 v[114:117], v[114:115], off offset:2048
	s_nop 0
	global_load_dwordx4 v[118:121], v[118:119], off offset:2560
	v_addc_co_u32_e32 v125, vcc, 0, v123, vcc
	s_nop 0
	s_waitcnt vmcnt(14)
	v_add_co_u32_e32 v126, vcc, 0x23000, v122
	s_nop 1
	v_addc_co_u32_e32 v127, vcc, 0, v123, vcc
	global_load_dwordx4 v[122:125], v[124:125], off offset:3072
	s_nop 0
	global_load_dwordx4 v[126:129], v[126:127], off offset:3584

.LBB0_754:
	s_or_b64 exec, exec, s[20:21]
	v_add_u32_e32 v206, 0x4000, v1
	v_ashrrev_i32_e32 v207, 31, v206
	v_lshlrev_b64 v[208:209], 12, v[206:207]
	v_lshlrev_b64 v[206:207], 11, v[206:207]
	v_lshl_add_u64 v[206:207], v[152:153], 0, v[206:207]
	v_lshl_add_u64 v[208:209], v[148:149], 0, v[208:209]
	v_lshl_add_u64 v[206:207], v[206:207], 0, s[18:19]
	v_cndmask_b32_e64 v207, v207, v209, s[4:5]
	v_cndmask_b32_e64 v206, v206, v208, s[4:5]
	v_pk_mul_f32 v[208:209], v[186:187], v[222:223]
	v_mov_b32_e32 v221, v142
	v_add_f32_e32 v135, v34, v208
	v_add_f32_e32 v135, v209, v135
	v_pk_mul_f32 v[208:209], v[188:189], v[138:139]
	v_mov_b32_e32 v143, v223
	v_add_f32_e32 v137, v35, v208
	v_add_f32_e32 v137, v209, v137
	v_pk_mul_f32 v[208:209], v[176:177], v[228:229]
	v_pk_mul_f32 v[142:143], v[10:11], v[142:143]
	v_add_f32_e32 v138, v36, v208
	v_add_f32_e32 v145, v209, v138
	v_pk_mul_f32 v[208:209], v[180:181], v[140:141]
	v_add_f32_e32 v143, v34, v143
	v_add_f32_e32 v138, v37, v208
	v_add_f32_e32 v140, v209, v138
	v_pk_mul_f32 v[208:209], v[168:169], v[224:225]
	v_add_f32_e32 v215, v142, v143
	v_add_f32_e32 v138, v38, v208
	v_add_f32_e32 v150, v209, v138
	v_pk_mul_f32 v[208:209], v[170:171], v[130:131]
	v_pk_mul_f32 v[226:227], v[162:163], v[132:133]
	v_add_f32_e32 v130, v39, v208
	v_add_f32_e32 v130, v209, v130
	v_pk_mul_f32 v[208:209], v[160:161], v[218:219]
	v_add_f32_e32 v132, v41, v226
	v_add_f32_e32 v138, v40, v208
	v_add_f32_e32 v217, v209, v138
	s_waitcnt vmcnt(15)
	v_lshlrev_b32_e32 v209, 16, v62
	v_mov_b32_e32 v220, v209
	v_pk_mul_f32 v[230:231], v[182:183], v[220:221]
	s_waitcnt vmcnt(14)
	v_lshlrev_b32_e32 v208, 16, v66
	v_add_f32_e32 v135, v231, v135
	v_add_f32_e32 v135, v230, v135
	v_mul_f32_e32 v138, 0xbfb8aa3b, v135
	v_exp_f32_e32 v138, v138
	v_mov_b32_e32 v223, v210
	v_add_f32_e32 v132, v227, v132
	s_mov_b64 s[22:23], -1
	v_add_f32_e32 v138, 1.0, v138
	v_pk_mul_f32 v[142:143], v[182:183], v[208:209]
	v_add_f32_e32 v143, v143, v215
	v_add_f32_e32 v142, v142, v143
	v_mul_f32_e32 v143, 0xbfb8aa3b, v142
	v_exp_f32_e32 v143, v143
	s_nop 0
	v_add_f32_e32 v215, 1.0, v143
	v_rcp_f32_e32 v211, v138
	s_nop 0
	v_mul_f32_e32 v135, v135, v211
	v_and_b32_e32 v143, 0xffff0000, v62
	v_mov_b32_e32 v222, v143
	v_pk_mul_f32 v[226:227], v[184:185], v[222:223]
	v_add_f32_e32 v137, v227, v137
	v_add_f32_e32 v137, v226, v137
	v_mul_f32_e32 v211, 0xbfb8aa3b, v137
	v_exp_f32_e32 v213, v211
	v_mov_b32_e32 v211, v139
	v_rcp_f32_e32 v138, v215
	s_nop 0
	v_mul_f32_e32 v235, v142, v138
	v_pk_mul_f32 v[138:139], v[2:3], v[210:211]
	v_add_f32_e32 v210, 1.0, v213
	v_add_f32_e32 v139, v35, v139
	v_add_f32_e32 v215, v138, v139
	v_and_b32_e32 v142, 0xffff0000, v66
	v_pk_mul_f32 v[138:139], v[184:185], v[142:143]
	v_add_f32_e32 v139, v139, v215
	v_add_f32_e32 v139, v138, v139
	v_mul_f32_e32 v138, 0xbfb8aa3b, v139
	v_exp_f32_e32 v138, v138
	s_nop 0
	v_add_f32_e32 v215, 1.0, v138
	v_rcp_f32_e32 v138, v210
	s_nop 0
	v_mul_f32_e32 v137, v137, v138
	v_cvt_pk_bf16_f32 v138, v135, v137
	v_lshlrev_b32_e32 v211, 16, v63
	v_mov_b32_e32 v226, v211
	v_mov_b32_e32 v227, v144
	v_pk_mul_f32 v[230:231], v[172:173], v[226:227]
	v_rcp_f32_e32 v135, v215
	s_nop 0
	v_mul_f32_e32 v238, v139, v135
	v_add_f32_e32 v137, v231, v145
	v_add_f32_e32 v137, v230, v137
	v_mul_f32_e32 v145, 0xbfb8aa3b, v137
	v_exp_f32_e32 v210, v145
	v_mov_b32_e32 v145, v229
	v_pk_mul_f32 v[144:145], v[12:13], v[144:145]
	v_mov_b32_e32 v229, v212
	v_add_f32_e32 v135, 1.0, v210
	v_add_f32_e32 v145, v36, v145
	v_add_f32_e32 v215, v144, v145
	v_lshlrev_b32_e32 v210, 16, v67
	v_pk_mul_f32 v[144:145], v[172:173], v[210:211]
	v_add_f32_e32 v145, v145, v215
	v_add_f32_e32 v144, v144, v145
	v_mul_f32_e32 v145, 0xbfb8aa3b, v144
	v_exp_f32_e32 v145, v145
	s_nop 0
	v_add_f32_e32 v215, 1.0, v145
	v_rcp_f32_e32 v139, v135
	s_nop 0
	v_mul_f32_e32 v135, v137, v139
	v_and_b32_e32 v145, 0xffff0000, v63
	v_mov_b32_e32 v228, v145
	v_pk_mul_f32 v[230:231], v[174:175], v[228:229]
	v_add_f32_e32 v139, v231, v140
	v_add_f32_e32 v139, v230, v139
	v_mul_f32_e32 v140, 0xbfb8aa3b, v139
	v_exp_f32_e32 v218, v140
	v_rcp_f32_e32 v137, v215
	s_nop 0
	v_mul_f32_e32 v239, v144, v137
	v_mov_b32_e32 v213, v141
	v_pk_mul_f32 v[140:141], v[4:5], v[212:213]
	v_add_f32_e32 v137, 1.0, v218
	v_add_f32_e32 v141, v37, v141
	v_add_f32_e32 v215, v140, v141
	v_and_b32_e32 v144, 0xffff0000, v67
	v_pk_mul_f32 v[140:141], v[174:175], v[144:145]
	v_add_f32_e32 v141, v141, v215
	v_add_f32_e32 v215, v140, v141
	v_mul_f32_e32 v140, 0xbfb8aa3b, v215
	v_exp_f32_e32 v140, v140
	s_nop 0
	v_add_f32_e32 v212, 1.0, v140
	v_rcp_f32_e32 v141, v137
	s_nop 0
	v_mul_f32_e32 v137, v139, v141
	v_cvt_pk_bf16_f32 v139, v135, v137
	v_lshlrev_b32_e32 v213, 16, v64
	v_mov_b32_e32 v230, v213
	v_mov_b32_e32 v231, v134
	v_pk_mul_f32 v[140:141], v[164:165], v[230:231]
	v_add_f32_e32 v137, v141, v150
	v_add_f32_e32 v137, v140, v137
	v_mul_f32_e32 v140, 0xbfb8aa3b, v137
	v_exp_f32_e32 v140, v140
	v_rcp_f32_e32 v135, v212
	s_nop 0
	v_mul_f32_e32 v150, v215, v135
	v_mov_b32_e32 v135, v225
	v_pk_mul_f32 v[134:135], v[14:15], v[134:135]
	v_add_f32_e32 v140, 1.0, v140
	v_add_f32_e32 v135, v38, v135
	v_add_f32_e32 v218, v134, v135
	v_lshlrev_b32_e32 v212, 16, v68
	v_pk_mul_f32 v[134:135], v[164:165], v[212:213]
	v_add_f32_e32 v135, v135, v218
	v_add_f32_e32 v134, v134, v135
	v_mul_f32_e32 v135, 0xbfb8aa3b, v134
	v_exp_f32_e32 v135, v135
	s_nop 0
	v_add_f32_e32 v218, 1.0, v135
	v_rcp_f32_e32 v141, v140
	s_nop 0
	v_mul_f32_e32 v137, v137, v141
	v_mov_b32_e32 v225, v214
	v_and_b32_e32 v135, 0xffff0000, v64
	v_mov_b32_e32 v224, v135
	v_pk_mul_f32 v[140:141], v[166:167], v[224:225]
	v_rcp_f32_e32 v215, v218
	s_nop 0
	v_mul_f32_e32 v240, v134, v215
	v_add_f32_e32 v130, v141, v130
	v_add_f32_e32 v140, v140, v130
	v_mul_f32_e32 v130, 0xbfb8aa3b, v140
	v_exp_f32_e32 v141, v130
	v_mov_b32_e32 v215, v131
	v_pk_mul_f32 v[130:131], v[6:7], v[214:215]
	v_and_b32_e32 v134, 0xffff0000, v68
	v_add_f32_e32 v141, 1.0, v141
	v_add_f32_e32 v131, v39, v131
	v_add_f32_e32 v218, v130, v131
	v_pk_mul_f32 v[130:131], v[166:167], v[134:135]
	v_add_f32_e32 v131, v131, v218
	v_add_f32_e32 v218, v130, v131
	v_mul_f32_e32 v130, 0xbfb8aa3b, v218
	v_exp_f32_e32 v130, v130
	s_nop 0
	v_add_f32_e32 v214, 1.0, v130
	v_rcp_f32_e32 v131, v141
	s_nop 0
	v_mul_f32_e32 v131, v140, v131
	v_cvt_pk_bf16_f32 v140, v137, v131
	v_lshlrev_b32_e32 v215, 16, v65
	v_mov_b32_e32 v236, v215
	v_mov_b32_e32 v237, v136
	v_pk_mul_f32 v[130:131], v[156:157], v[236:237]
	v_rcp_f32_e32 v137, v214
	s_nop 0
	v_mul_f32_e32 v241, v218, v137
	v_add_f32_e32 v131, v131, v217
	v_add_f32_e32 v141, v130, v131
	v_mul_f32_e32 v130, 0xbfb8aa3b, v141
	v_exp_f32_e32 v217, v130
	v_mov_b32_e32 v137, v219
	v_pk_mul_f32 v[130:131], v[16:17], v[136:137]
	v_lshlrev_b32_e32 v214, 16, v69
	v_add_f32_e32 v136, 1.0, v217
	v_add_f32_e32 v131, v40, v131
	v_add_f32_e32 v218, v130, v131
	v_pk_mul_f32 v[130:131], v[156:157], v[214:215]
	v_add_f32_e32 v131, v131, v218
	v_add_f32_e32 v243, v130, v131
	v_mul_f32_e32 v130, 0xbfb8aa3b, v243
	v_exp_f32_e32 v130, v130
	s_nop 0
	v_add_f32_e32 v244, 1.0, v130
	v_rcp_f32_e32 v131, v136
	s_nop 0
	v_mul_f32_e32 v141, v141, v131
	v_mov_b32_e32 v219, v216
	v_and_b32_e32 v137, 0xffff0000, v65
	v_mov_b32_e32 v218, v137
	v_pk_mul_f32 v[130:131], v[158:159], v[218:219]
	v_mov_b32_e32 v217, v133
	v_add_f32_e32 v131, v131, v132
	v_add_f32_e32 v132, v130, v131
	v_mul_f32_e32 v130, 0xbfb8aa3b, v132
	v_exp_f32_e32 v242, v130
	v_pk_mul_f32 v[130:131], v[8:9], v[216:217]
	v_rcp_f32_e32 v136, v244
	s_nop 0
	v_mul_f32_e32 v243, v243, v136
	v_add_f32_e32 v131, v41, v131
	v_add_f32_e32 v133, 1.0, v242
	v_add_f32_e32 v242, v130, v131
	v_and_b32_e32 v136, 0xffff0000, v69
	v_pk_mul_f32 v[130:131], v[158:159], v[136:137]
	v_add_f32_e32 v131, v131, v242
	v_add_f32_e32 v130, v130, v131
	v_mul_f32_e32 v131, 0xbfb8aa3b, v130
	v_exp_f32_e32 v131, v131
	v_rcp_f32_e32 v216, v133
	s_nop 0
	v_mul_f32_e32 v132, v132, v216
	v_cvt_pk_bf16_f32 v141, v141, v132
	v_add_f32_e32 v131, 1.0, v131
	global_store_dwordx4 v[206:207], v[138:141], off
	v_rcp_f32_e32 v132, v131
	s_nop 0
	v_mul_f32_e32 v133, v130, v132
	v_cvt_pk_bf16_f32 v131, v239, v150
	v_lshlrev_b32_e32 v150, 1, v190
	v_cvt_pk_bf16_f32 v130, v235, v238
	v_lshl_add_u64 v[140:141], v[206:207], 0, v[150:151]
	v_cvt_pk_bf16_f32 v132, v240, v241
	v_cvt_pk_bf16_f32 v133, v243, v133
	global_store_dwordx4 v[140:141], v[130:133], off
	s_waitcnt vmcnt(15)
	v_lshlrev_b32_e32 v138, 16, v78
	v_pk_mul_f32 v[130:131], v[10:11], v[220:221]
	v_mov_b32_e32 v132, v138
	v_add_f32_e32 v131, v34, v131
	v_add_f32_e32 v139, v130, v131
	v_pk_mul_f32 v[130:131], v[2:3], v[222:223]
	v_mov_b32_e32 v133, v208
	v_add_f32_e32 v131, v35, v131
	v_add_f32_e32 v216, v130, v131
	v_pk_mul_f32 v[130:131], v[12:13], v[226:227]
	v_pk_mul_f32 v[132:133], v[182:183], v[132:133]
	v_add_f32_e32 v131, v36, v131
	v_add_f32_e32 v133, v133, v139
	v_add_f32_e32 v217, v130, v131
	v_pk_mul_f32 v[130:131], v[4:5], v[228:229]
	v_add_f32_e32 v132, v132, v133
	v_add_f32_e32 v131, v37, v131
	v_mul_f32_e32 v133, 0xbfb8aa3b, v132
	v_add_f32_e32 v220, v130, v131
	v_pk_mul_f32 v[130:131], v[14:15], v[230:231]
	v_exp_f32_e32 v133, v133
	v_add_f32_e32 v131, v38, v131
	v_add_f32_e32 v221, v130, v131
	v_pk_mul_f32 v[130:131], v[6:7], v[224:225]
	v_add_f32_e32 v133, 1.0, v133
	v_add_f32_e32 v131, v39, v131
	v_add_f32_e32 v223, v130, v131
	v_pk_mul_f32 v[130:131], v[16:17], v[236:237]
	v_lshl_add_u64 v[228:229], v[140:141], 0, v[200:201]
	v_add_f32_e32 v131, v40, v131
	v_add_f32_e32 v225, v130, v131
	v_pk_mul_f32 v[130:131], v[8:9], v[218:219]
	v_add_f32_e32 v131, v41, v131
	v_add_f32_e32 v235, v130, v131
	v_pk_mul_f32 v[130:131], v[10:11], v[208:209]
	s_waitcnt vmcnt(14)
	v_lshlrev_b32_e32 v139, 16, v58
	v_add_f32_e32 v131, v34, v131
	v_add_f32_e32 v209, v131, v130
	v_pk_mul_f32 v[130:131], v[18:19], v[138:139]
	v_add_f32_e32 v130, v209, v130
	v_add_f32_e32 v209, v130, v131
	v_mul_f32_e32 v130, 0xbfb8aa3b, v209
	v_exp_f32_e32 v130, v130
	s_nop 0
	v_add_f32_e32 v218, 1.0, v130
	v_rcp_f32_e32 v131, v133
	s_nop 0
	v_mul_f32_e32 v132, v132, v131
	v_and_b32_e32 v140, 0xffff0000, v78
	v_mov_b32_e32 v130, v140
	v_mov_b32_e32 v131, v142
	v_pk_mul_f32 v[130:131], v[184:185], v[130:131]
	s_nop 0
	v_add_f32_e32 v131, v131, v216
	v_add_f32_e32 v216, v130, v131
	v_mul_f32_e32 v130, 0xbfb8aa3b, v216
	v_exp_f32_e32 v219, v130
	v_rcp_f32_e32 v130, v218
	s_nop 0
	v_mul_f32_e32 v209, v209, v130
	v_pk_mul_f32 v[130:131], v[2:3], v[142:143]
	v_add_f32_e32 v133, 1.0, v219
	v_add_f32_e32 v131, v35, v131
	v_add_f32_e32 v219, v131, v130
	v_and_b32_e32 v141, 0xffff0000, v58
	v_pk_mul_f32 v[130:131], v[26:27], v[140:141]
	v_add_f32_e32 v130, v219, v130
	v_add_f32_e32 v131, v130, v131
	v_mul_f32_e32 v130, 0xbfb8aa3b, v131
	v_exp_f32_e32 v130, v130
	s_nop 0
	v_add_f32_e32 v219, 1.0, v130
	v_rcp_f32_e32 v130, v133
	s_nop 0
	v_mul_f32_e32 v130, v216, v130
	v_cvt_pk_bf16_f32 v130, v132, v130
	v_lshlrev_b32_e32 v216, 16, v79
	v_mov_b32_e32 v132, v216
	v_mov_b32_e32 v133, v210
	v_pk_mul_f32 v[132:133], v[172:173], v[132:133]
	s_nop 0
	v_add_f32_e32 v133, v133, v217
	v_add_f32_e32 v222, v132, v133
	v_mul_f32_e32 v132, 0xbfb8aa3b, v222
	v_exp_f32_e32 v217, v132
	v_rcp_f32_e32 v132, v219
	s_nop 0
	v_mul_f32_e32 v143, v131, v132
	v_pk_mul_f32 v[132:133], v[12:13], v[210:211]
	v_add_f32_e32 v131, 1.0, v217
	v_add_f32_e32 v133, v36, v133
	v_add_f32_e32 v219, v133, v132
	v_lshlrev_b32_e32 v217, 16, v59
	v_pk_mul_f32 v[132:133], v[20:21], v[216:217]
	v_add_f32_e32 v132, v219, v132
	v_add_f32_e32 v219, v132, v133
	v_mul_f32_e32 v132, 0xbfb8aa3b, v219
	v_exp_f32_e32 v132, v132
	s_nop 0
	v_add_f32_e32 v211, 1.0, v132
	v_rcp_f32_e32 v133, v131
	s_nop 0
	v_mul_f32_e32 v131, v222, v133
	v_and_b32_e32 v218, 0xffff0000, v79
	v_mov_b32_e32 v132, v218
	v_mov_b32_e32 v133, v144
	v_pk_mul_f32 v[132:133], v[174:175], v[132:133]
	s_nop 0
	v_add_f32_e32 v133, v133, v220
	v_add_f32_e32 v220, v132, v133
	v_mul_f32_e32 v132, 0xbfb8aa3b, v220
	v_exp_f32_e32 v227, v132
	v_rcp_f32_e32 v132, v211
	s_nop 0
	v_mul_f32_e32 v211, v219, v132
	v_pk_mul_f32 v[132:133], v[4:5], v[144:145]
	v_add_f32_e32 v145, 1.0, v227
	v_add_f32_e32 v133, v37, v133
	v_add_f32_e32 v226, v133, v132
	v_and_b32_e32 v219, 0xffff0000, v59
	v_pk_mul_f32 v[132:133], v[28:29], v[218:219]
	v_add_f32_e32 v132, v226, v132
	v_add_f32_e32 v226, v132, v133
	v_mul_f32_e32 v132, 0xbfb8aa3b, v226
	v_exp_f32_e32 v132, v132
	s_nop 0
	v_add_f32_e32 v222, 1.0, v132
	v_rcp_f32_e32 v133, v145
	s_nop 0
	v_mul_f32_e32 v133, v220, v133
	v_cvt_pk_bf16_f32 v131, v131, v133
	v_lshlrev_b32_e32 v220, 16, v80
	v_mov_b32_e32 v132, v220
	v_mov_b32_e32 v133, v212
	v_pk_mul_f32 v[132:133], v[164:165], v[132:133]
	s_nop 0
	v_add_f32_e32 v133, v133, v221
	v_add_f32_e32 v230, v132, v133
	v_mul_f32_e32 v132, 0xbfb8aa3b, v230
	v_exp_f32_e32 v221, v132
	v_rcp_f32_e32 v132, v222
	s_nop 0
	v_mul_f32_e32 v145, v226, v132
	v_pk_mul_f32 v[132:133], v[14:15], v[212:213]
	v_add_f32_e32 v213, 1.0, v221
	v_add_f32_e32 v133, v38, v133
	v_add_f32_e32 v226, v133, v132
	v_lshlrev_b32_e32 v221, 16, v60
	v_pk_mul_f32 v[132:133], v[22:23], v[220:221]
	v_add_f32_e32 v132, v226, v132
	v_add_f32_e32 v226, v132, v133
	v_mul_f32_e32 v132, 0xbfb8aa3b, v226
	v_exp_f32_e32 v132, v132
	s_nop 0
	v_add_f32_e32 v227, 1.0, v132
	v_rcp_f32_e32 v133, v213
	s_nop 0
	v_mul_f32_e32 v213, v230, v133
	v_and_b32_e32 v222, 0xffff0000, v80
	v_mov_b32_e32 v132, v222
	v_mov_b32_e32 v133, v134
	v_pk_mul_f32 v[132:133], v[166:167], v[132:133]
	s_nop 0
	v_add_f32_e32 v133, v133, v223
	v_add_f32_e32 v231, v132, v133
	v_mul_f32_e32 v132, 0xbfb8aa3b, v231
	v_exp_f32_e32 v223, v132
	v_rcp_f32_e32 v132, v227
	s_nop 0
	v_mul_f32_e32 v236, v226, v132
	v_pk_mul_f32 v[132:133], v[6:7], v[134:135]
	v_add_f32_e32 v135, 1.0, v223
	v_add_f32_e32 v133, v39, v133
	v_add_f32_e32 v227, v133, v132
	v_and_b32_e32 v223, 0xffff0000, v60
	v_pk_mul_f32 v[132:133], v[30:31], v[222:223]
	v_add_f32_e32 v132, v227, v132
	v_add_f32_e32 v133, v132, v133
	v_mul_f32_e32 v132, 0xbfb8aa3b, v133
	v_exp_f32_e32 v132, v132
	s_nop 0
	v_add_f32_e32 v230, 1.0, v132
	v_rcp_f32_e32 v132, v135
	s_nop 0
	v_mul_f32_e32 v132, v231, v132
	v_cvt_pk_bf16_f32 v132, v213, v132
	v_lshlrev_b32_e32 v224, 16, v81
	v_mov_b32_e32 v226, v224
	v_mov_b32_e32 v227, v214
	v_pk_mul_f32 v[226:227], v[156:157], v[226:227]
	v_add_f32_e32 v225, v227, v225
	v_add_f32_e32 v231, v226, v225
	v_mul_f32_e32 v225, 0xbfb8aa3b, v231
	v_exp_f32_e32 v225, v225
	v_rcp_f32_e32 v135, v230
	s_nop 0
	v_mul_f32_e32 v135, v133, v135
	v_pk_mul_f32 v[226:227], v[16:17], v[214:215]
	v_add_f32_e32 v133, 1.0, v225
	v_add_f32_e32 v225, v40, v227
	v_add_f32_e32 v230, v225, v226
	v_lshlrev_b32_e32 v225, 16, v61
	v_pk_mul_f32 v[226:227], v[24:25], v[224:225]
	v_add_f32_e32 v226, v230, v226
	v_add_f32_e32 v227, v226, v227
	v_mul_f32_e32 v226, 0xbfb8aa3b, v227
	v_exp_f32_e32 v226, v226
	s_nop 0
	v_add_f32_e32 v237, 1.0, v226
	v_rcp_f32_e32 v213, v133
	s_nop 0
	v_mul_f32_e32 v133, v231, v213
	v_mov_b32_e32 v231, v136
	v_and_b32_e32 v226, 0xffff0000, v81
	v_mov_b32_e32 v230, v226
	v_pk_mul_f32 v[230:231], v[158:159], v[230:231]
	v_add_f32_e32 v231, v231, v235
	v_add_f32_e32 v235, v230, v231
	v_mul_f32_e32 v230, 0xbfb8aa3b, v235
	v_exp_f32_e32 v238, v230
	v_pk_mul_f32 v[230:231], v[8:9], v[136:137]
	v_rcp_f32_e32 v213, v237
	s_nop 0
	v_mul_f32_e32 v213, v227, v213
	v_add_f32_e32 v227, v41, v231
	v_add_f32_e32 v137, 1.0, v238
	v_add_f32_e32 v238, v227, v230
	v_and_b32_e32 v227, 0xffff0000, v61
	v_pk_mul_f32 v[230:231], v[32:33], v[226:227]
	v_add_f32_e32 v230, v238, v230
	v_add_f32_e32 v230, v230, v231
	v_mul_f32_e32 v231, 0xbfb8aa3b, v230
	v_exp_f32_e32 v231, v231
	v_rcp_f32_e32 v215, v137
	s_nop 0
	v_mul_f32_e32 v137, v235, v215
	v_cvt_pk_bf16_f32 v133, v133, v137
	v_add_f32_e32 v231, 1.0, v231
	global_store_dwordx4 v[228:229], v[130:133], off
	v_mov_b32_e32 v215, v224
	v_mov_b32_e32 v137, v226
	v_rcp_f32_e32 v130, v231
	s_nop 0
	v_mul_f32_e32 v133, v230, v130
	v_cvt_pk_bf16_f32 v130, v209, v143
	v_cvt_pk_bf16_f32 v131, v211, v145
	v_lshl_add_u64 v[230:231], v[206:207], 0, v[192:193]
	v_mov_b32_e32 v209, v138
	v_cvt_pk_bf16_f32 v132, v236, v135
	v_cvt_pk_bf16_f32 v133, v213, v133
	global_store_dwordx4 v[230:231], v[130:133], off
	v_mov_b32_e32 v143, v140
	v_mov_b32_e32 v211, v216
	v_pk_mul_f32 v[130:131], v[186:187], v[208:209]
	v_mov_b32_e32 v145, v218
	v_add_f32_e32 v130, v34, v130
	v_add_f32_e32 v208, v130, v131
	v_pk_mul_f32 v[130:131], v[188:189], v[142:143]
	v_mov_b32_e32 v213, v220
	v_add_f32_e32 v130, v35, v130
	v_add_f32_e32 v142, v130, v131
	v_pk_mul_f32 v[130:131], v[176:177], v[210:211]
	s_waitcnt vmcnt(14)
	v_lshlrev_b32_e32 v211, 16, v54
	v_add_f32_e32 v130, v36, v130
	v_add_f32_e32 v143, v130, v131
	v_pk_mul_f32 v[130:131], v[180:181], v[144:145]
	v_lshlrev_b32_e32 v210, 16, v74
	v_add_f32_e32 v130, v37, v130
	v_add_f32_e32 v235, v130, v131
	v_pk_mul_f32 v[130:131], v[168:169], v[212:213]
	v_pk_mov_b32 v[212:213], v[138:139], v[210:211] op_sel:[1,0]
	v_add_f32_e32 v130, v38, v130
	v_pk_mul_f32 v[132:133], v[18:19], v[212:213]
	v_mov_b32_e32 v135, v222
	v_add_f32_e32 v132, v208, v132
	v_add_f32_e32 v132, v132, v133
	v_mul_f32_e32 v133, 0xbfb8aa3b, v132
	v_exp_f32_e32 v133, v133
	v_add_f32_e32 v236, v130, v131
	v_pk_mul_f32 v[130:131], v[170:171], v[134:135]
	v_and_b32_e32 v209, 0xffff0000, v54
	v_add_f32_e32 v130, v39, v130
	v_add_f32_e32 v134, v130, v131
	v_pk_mul_f32 v[130:131], v[160:161], v[214:215]
	v_add_f32_e32 v133, 1.0, v133
	v_add_f32_e32 v130, v40, v130
	v_add_f32_e32 v237, v130, v131
	v_pk_mul_f32 v[130:131], v[162:163], v[136:137]
	v_add_f32_e32 v130, v41, v130
	v_add_f32_e32 v238, v130, v131
	v_pk_mul_f32 v[130:131], v[186:187], v[138:139]
	v_add_f32_e32 v130, v34, v130
	v_add_f32_e32 v137, v130, v131
	v_pk_mul_f32 v[130:131], v[18:19], v[210:211]
	v_add_f32_e32 v130, v137, v130
	v_add_f32_e32 v137, v130, v131
	v_mul_f32_e32 v130, 0xbfb8aa3b, v137
	v_exp_f32_e32 v130, v130
	s_nop 0
	v_add_f32_e32 v135, 1.0, v130
	v_rcp_f32_e32 v131, v133
	s_nop 0
	v_mul_f32_e32 v132, v132, v131
	v_and_b32_e32 v208, 0xffff0000, v74
	v_lshl_add_u64 v[214:215], v[228:229], 0, v[202:203]
	v_pk_mov_b32 v[228:229], v[140:141], v[208:209] op_sel:[1,0]
	v_pk_mul_f32 v[130:131], v[26:27], v[228:229]
	v_lshlrev_b32_e32 v145, 16, v55
	v_add_f32_e32 v130, v142, v130
	v_add_f32_e32 v139, v130, v131
	v_mul_f32_e32 v130, 0xbfb8aa3b, v139
	v_exp_f32_e32 v130, v130
	v_rcp_f32_e32 v131, v135
	s_nop 0
	v_mul_f32_e32 v239, v137, v131
	v_lshlrev_b32_e32 v144, 16, v75
	v_add_f32_e32 v133, 1.0, v130
	v_pk_mul_f32 v[130:131], v[188:189], v[140:141]
	v_add_f32_e32 v130, v35, v130
	v_add_f32_e32 v137, v130, v131
	v_pk_mul_f32 v[130:131], v[26:27], v[208:209]
	v_add_f32_e32 v130, v137, v130
	v_add_f32_e32 v131, v130, v131
	v_mul_f32_e32 v130, 0xbfb8aa3b, v131
	v_exp_f32_e32 v130, v130
	s_nop 0
	v_add_f32_e32 v137, 1.0, v130
	v_rcp_f32_e32 v130, v133
	s_nop 0
	v_mul_f32_e32 v130, v139, v130
	v_cvt_pk_bf16_f32 v130, v132, v130
	v_pk_mov_b32 v[230:231], v[216:217], v[144:145] op_sel:[1,0]
	v_pk_mul_f32 v[132:133], v[20:21], v[230:231]
	v_and_b32_e32 v142, 0xffff0000, v75
	v_add_f32_e32 v132, v143, v132
	v_add_f32_e32 v138, v132, v133
	v_mul_f32_e32 v132, 0xbfb8aa3b, v138
	v_exp_f32_e32 v132, v132
	v_rcp_f32_e32 v133, v137
	s_nop 0
	v_mul_f32_e32 v240, v131, v133
	v_and_b32_e32 v143, 0xffff0000, v55
	v_add_f32_e32 v131, 1.0, v132
	v_pk_mul_f32 v[132:133], v[176:177], v[216:217]
	v_add_f32_e32 v132, v36, v132
	v_add_f32_e32 v137, v132, v133
	v_pk_mul_f32 v[132:133], v[20:21], v[144:145]
	v_add_f32_e32 v132, v137, v132
	v_add_f32_e32 v137, v132, v133
	v_mul_f32_e32 v132, 0xbfb8aa3b, v137
	v_exp_f32_e32 v132, v132
	s_nop 0
	v_add_f32_e32 v135, 1.0, v132
	v_rcp_f32_e32 v133, v131
	s_nop 0
	v_mul_f32_e32 v131, v138, v133
	v_pk_mov_b32 v[216:217], v[218:219], v[142:143] op_sel:[1,0]
	v_pk_mul_f32 v[132:133], v[28:29], v[216:217]
	s_nop 0
	v_add_f32_e32 v132, v235, v132
	v_add_f32_e32 v140, v132, v133
	v_mul_f32_e32 v132, 0xbfb8aa3b, v140
	v_exp_f32_e32 v132, v132
	v_rcp_f32_e32 v133, v135
	s_nop 0
	v_mul_f32_e32 v235, v137, v133
	v_add_f32_e32 v135, 1.0, v132
	v_pk_mul_f32 v[132:133], v[180:181], v[218:219]
	v_add_f32_e32 v132, v37, v132
	v_add_f32_e32 v138, v132, v133
	v_pk_mul_f32 v[132:133], v[28:29], v[142:143]
	v_add_f32_e32 v132, v138, v132
	v_add_f32_e32 v138, v132, v133
	v_mul_f32_e32 v132, 0xbfb8aa3b, v138
	v_exp_f32_e32 v132, v132
	s_nop 0
	v_add_f32_e32 v136, 1.0, v132
	v_rcp_f32_e32 v133, v135
	s_nop 0
	v_mul_f32_e32 v133, v140, v133
	v_cvt_pk_bf16_f32 v131, v131, v133
	v_lshlrev_b32_e32 v141, 16, v56
	v_lshlrev_b32_e32 v140, 16, v76
	v_pk_mov_b32 v[218:219], v[220:221], v[140:141] op_sel:[1,0]
	v_pk_mul_f32 v[132:133], v[22:23], v[218:219]
	s_nop 0
	v_add_f32_e32 v132, v236, v132
	v_add_f32_e32 v236, v132, v133
	v_mul_f32_e32 v132, 0xbfb8aa3b, v236
	v_exp_f32_e32 v132, v132
	v_rcp_f32_e32 v133, v136
	s_nop 0
	v_mul_f32_e32 v241, v138, v133
	v_add_f32_e32 v135, 1.0, v132
	v_pk_mul_f32 v[132:133], v[168:169], v[220:221]
	v_add_f32_e32 v132, v38, v132
	v_add_f32_e32 v138, v132, v133
	v_pk_mul_f32 v[132:133], v[22:23], v[140:141]
	v_add_f32_e32 v132, v138, v132
	v_add_f32_e32 v242, v132, v133
	v_mul_f32_e32 v132, 0xbfb8aa3b, v242
	v_exp_f32_e32 v132, v132
	s_nop 0
	v_add_f32_e32 v136, 1.0, v132
	v_rcp_f32_e32 v133, v135
	s_nop 0
	v_mul_f32_e32 v135, v236, v133
	v_and_b32_e32 v139, 0xffff0000, v56
	v_and_b32_e32 v138, 0xffff0000, v76
	v_pk_mov_b32 v[220:221], v[222:223], v[138:139] op_sel:[1,0]
	v_pk_mul_f32 v[132:133], v[30:31], v[220:221]
	s_nop 0
	v_add_f32_e32 v132, v134, v132
	v_add_f32_e32 v134, v132, v133
	v_mul_f32_e32 v132, 0xbfb8aa3b, v134
	v_exp_f32_e32 v132, v132
	v_rcp_f32_e32 v133, v136
	s_nop 0
	v_mul_f32_e32 v242, v242, v133
	v_add_f32_e32 v136, 1.0, v132
	v_pk_mul_f32 v[132:133], v[170:171], v[222:223]
	v_add_f32_e32 v132, v39, v132
	v_add_f32_e32 v222, v132, v133
	v_pk_mul_f32 v[132:133], v[30:31], v[138:139]
	v_add_f32_e32 v132, v222, v132
	v_add_f32_e32 v133, v132, v133
	v_mul_f32_e32 v132, 0xbfb8aa3b, v133
	v_exp_f32_e32 v132, v132
	s_nop 0
	v_add_f32_e32 v244, 1.0, v132
	v_rcp_f32_e32 v132, v136
	s_nop 0
	v_mul_f32_e32 v132, v134, v132
	v_cvt_pk_bf16_f32 v132, v135, v132
	v_lshlrev_b32_e32 v137, 16, v57
	v_lshlrev_b32_e32 v136, 16, v77
	v_pk_mov_b32 v[222:223], v[224:225], v[136:137] op_sel:[1,0]
	s_nop 0
	v_pk_mul_f32 v[134:135], v[24:25], v[222:223]
	s_nop 0
	v_add_f32_e32 v134, v237, v134
	v_add_f32_e32 v237, v134, v135
	v_mul_f32_e32 v134, 0xbfb8aa3b, v237
	v_exp_f32_e32 v134, v134
	v_rcp_f32_e32 v135, v244
	s_nop 0
	v_mul_f32_e32 v243, v133, v135
	v_add_f32_e32 v133, 1.0, v134
	v_pk_mul_f32 v[134:135], v[160:161], v[224:225]
	v_add_f32_e32 v134, v40, v134
	v_add_f32_e32 v224, v134, v135
	v_pk_mul_f32 v[134:135], v[24:25], v[136:137]
	v_add_f32_e32 v134, v224, v134
	v_add_f32_e32 v246, v134, v135
	v_mul_f32_e32 v134, 0xbfb8aa3b, v246
	v_exp_f32_e32 v134, v134
	s_nop 0
	v_add_f32_e32 v247, 1.0, v134
	v_rcp_f32_e32 v135, v133
	s_nop 0
	v_mul_f32_e32 v133, v237, v135
	v_and_b32_e32 v135, 0xffff0000, v57
	v_and_b32_e32 v134, 0xffff0000, v77
	v_pk_mov_b32 v[224:225], v[226:227], v[134:135] op_sel:[1,0]
	v_pk_mul_f32 v[226:227], v[162:163], v[226:227]
	v_pk_mul_f32 v[236:237], v[32:33], v[224:225]
	v_add_f32_e32 v226, v41, v226
	v_add_f32_e32 v236, v238, v236
	v_add_f32_e32 v236, v236, v237
	v_mul_f32_e32 v237, 0xbfb8aa3b, v236
	v_exp_f32_e32 v237, v237
	v_rcp_f32_e32 v238, v247
	s_nop 0
	v_mul_f32_e32 v238, v246, v238
	v_add_f32_e32 v246, v226, v227
	v_add_f32_e32 v237, 1.0, v237
	v_pk_mul_f32 v[226:227], v[32:33], v[134:135]
	v_add_f32_e32 v226, v246, v226
	v_add_f32_e32 v226, v226, v227
	v_mul_f32_e32 v227, 0xbfb8aa3b, v226
	v_exp_f32_e32 v227, v227
	v_rcp_f32_e32 v244, v237
	s_nop 0
	v_mul_f32_e32 v236, v236, v244
	v_cvt_pk_bf16_f32 v133, v133, v236
	v_add_f32_e32 v227, 1.0, v227
	global_store_dwordx4 v[214:215], v[130:133], off
	v_lshl_add_u64 v[214:215], v[206:207], 0, v[194:195]
	s_nop 0
	v_rcp_f32_e32 v130, v227
	s_nop 0
	v_mul_f32_e32 v133, v226, v130
	v_cvt_pk_bf16_f32 v130, v239, v240
	v_cvt_pk_bf16_f32 v131, v235, v241
	v_cvt_pk_bf16_f32 v132, v242, v243
	v_cvt_pk_bf16_f32 v133, v238, v133
	global_store_dwordx4 v[214:215], v[130:133], off
	s_nop 1
	v_pk_mul_f32 v[130:131], v[186:187], v[212:213]
	s_waitcnt vmcnt(15)
	v_lshlrev_b32_e32 v132, 16, v70
	v_add_f32_e32 v130, v34, v130
	v_add_f32_e32 v214, v130, v131
	v_pk_mul_f32 v[130:131], v[188:189], v[228:229]
	s_waitcnt vmcnt(14)
	v_lshlrev_b32_e32 v133, 16, v82
	v_add_f32_e32 v130, v35, v130
	v_add_f32_e32 v215, v130, v131
	v_pk_mul_f32 v[130:131], v[176:177], v[230:231]
	v_pk_mov_b32 v[212:213], v[210:211], v[132:133] op_sel:[1,0]
	v_add_f32_e32 v130, v36, v130
	v_add_f32_e32 v226, v130, v131
	v_pk_mul_f32 v[130:131], v[180:181], v[216:217]
	v_pk_mul_f32 v[212:213], v[18:19], v[212:213]
	v_add_f32_e32 v130, v37, v130
	v_add_f32_e32 v212, v214, v212
	v_add_f32_e32 v216, v130, v131
	v_pk_mul_f32 v[130:131], v[168:169], v[218:219]
	v_add_f32_e32 v214, v212, v213
	v_add_f32_e32 v130, v38, v130
	v_mul_f32_e32 v212, 0xbfb8aa3b, v214
	v_add_f32_e32 v217, v130, v131
	v_pk_mul_f32 v[130:131], v[170:171], v[220:221]
	v_exp_f32_e32 v220, v212
	v_add_f32_e32 v130, v39, v130
	v_add_f32_e32 v218, v130, v131
	v_pk_mul_f32 v[130:131], v[160:161], v[222:223]
	v_add_f32_e32 v220, 1.0, v220
	v_add_f32_e32 v130, v40, v130
	v_add_f32_e32 v219, v130, v131
	v_pk_mul_f32 v[130:131], v[162:163], v[224:225]
	v_add_f32_e32 v130, v41, v130
	v_add_f32_e32 v221, v130, v131
	v_pk_mul_f32 v[130:131], v[186:187], v[210:211]
	v_add_f32_e32 v130, v34, v130
	v_add_f32_e32 v210, v130, v131
	v_pk_mul_f32 v[130:131], v[18:19], v[132:133]
	v_add_f32_e32 v130, v210, v130
	v_add_f32_e32 v210, v130, v131
	v_mul_f32_e32 v130, 0xbfb8aa3b, v210
	v_exp_f32_e32 v130, v130
	s_nop 0
	v_add_f32_e32 v211, 1.0, v130
	v_rcp_f32_e32 v131, v220
	s_nop 0
	v_mul_f32_e32 v214, v214, v131
	v_lshl_add_u64 v[212:213], v[206:207], 0, v[196:197]
	v_and_b32_e32 v131, 0xffff0000, v82
	v_and_b32_e32 v130, 0xffff0000, v70
	v_pk_mov_b32 v[132:133], v[208:209], v[130:131] op_sel:[1,0]
	v_pk_mul_f32 v[130:131], v[26:27], v[130:131]
	v_pk_mul_f32 v[132:133], v[26:27], v[132:133]
	s_nop 0
	v_add_f32_e32 v132, v215, v132
	v_add_f32_e32 v215, v132, v133
	v_mul_f32_e32 v132, 0xbfb8aa3b, v215
	v_exp_f32_e32 v132, v132
	v_rcp_f32_e32 v133, v211
	s_nop 0
	v_mul_f32_e32 v210, v210, v133
	v_add_f32_e32 v211, 1.0, v132
	v_pk_mul_f32 v[132:133], v[188:189], v[208:209]
	v_add_f32_e32 v132, v35, v132
	v_add_f32_e32 v132, v132, v133
	v_add_f32_e32 v130, v132, v130
	v_add_f32_e32 v131, v130, v131
	v_mul_f32_e32 v130, 0xbfb8aa3b, v131
	v_exp_f32_e32 v130, v130
	s_nop 0
	v_add_f32_e32 v220, 1.0, v130
	v_rcp_f32_e32 v130, v211
	s_nop 0
	v_mul_f32_e32 v130, v215, v130
	v_cvt_pk_bf16_f32 v130, v214, v130
	v_lshlrev_b32_e32 v132, 16, v71
	v_lshlrev_b32_e32 v133, 16, v83
	v_pk_mov_b32 v[208:209], v[144:145], v[132:133] op_sel:[1,0]
	v_pk_mul_f32 v[208:209], v[20:21], v[208:209]
	v_rcp_f32_e32 v211, v220
	s_nop 0
	v_mul_f32_e32 v211, v131, v211
	v_add_f32_e32 v208, v226, v208
	v_add_f32_e32 v208, v208, v209
	v_mul_f32_e32 v209, 0xbfb8aa3b, v208
	v_exp_f32_e32 v209, v209
	v_pk_mul_f32 v[144:145], v[176:177], v[144:145]
	v_pk_mul_f32 v[132:133], v[20:21], v[132:133]
	v_add_f32_e32 v144, v36, v144
	v_add_f32_e32 v131, 1.0, v209
	v_add_f32_e32 v144, v144, v145
	v_add_f32_e32 v132, v144, v132
	v_add_f32_e32 v220, v132, v133
	v_mul_f32_e32 v132, 0xbfb8aa3b, v220
	v_exp_f32_e32 v132, v132
	s_nop 0
	v_add_f32_e32 v209, 1.0, v132
	v_rcp_f32_e32 v133, v131
	s_nop 0
	v_mul_f32_e32 v131, v208, v133
	v_and_b32_e32 v133, 0xffff0000, v83
	v_and_b32_e32 v132, 0xffff0000, v71
	v_pk_mov_b32 v[144:145], v[142:143], v[132:133] op_sel:[1,0]
	v_pk_mul_f32 v[144:145], v[28:29], v[144:145]
	v_rcp_f32_e32 v208, v209
	s_nop 0
	v_mul_f32_e32 v208, v220, v208
	v_add_f32_e32 v144, v216, v144
	v_add_f32_e32 v144, v144, v145
	v_mul_f32_e32 v145, 0xbfb8aa3b, v144
	v_exp_f32_e32 v145, v145
	v_pk_mul_f32 v[142:143], v[180:181], v[142:143]
	v_pk_mul_f32 v[132:133], v[28:29], v[132:133]
	v_add_f32_e32 v142, v37, v142
	v_add_f32_e32 v145, 1.0, v145
	v_add_f32_e32 v142, v142, v143
	v_add_f32_e32 v132, v142, v132
	v_add_f32_e32 v216, v132, v133
	v_mul_f32_e32 v132, 0xbfb8aa3b, v216
	v_exp_f32_e32 v132, v132
	s_nop 0
	v_add_f32_e32 v209, 1.0, v132
	v_rcp_f32_e32 v133, v145
	s_nop 0
	v_mul_f32_e32 v133, v144, v133
	v_cvt_pk_bf16_f32 v131, v131, v133
	v_lshlrev_b32_e32 v132, 16, v72
	v_lshlrev_b32_e32 v133, 16, v84
	v_pk_mov_b32 v[142:143], v[140:141], v[132:133] op_sel:[1,0]
	v_pk_mul_f32 v[142:143], v[22:23], v[142:143]
	v_pk_mul_f32 v[140:141], v[168:169], v[140:141]
	v_add_f32_e32 v142, v217, v142
	v_add_f32_e32 v142, v142, v143
	v_mul_f32_e32 v143, 0xbfb8aa3b, v142
	v_exp_f32_e32 v143, v143
	v_rcp_f32_e32 v144, v209
	s_nop 0
	v_mul_f32_e32 v144, v216, v144
	v_add_f32_e32 v140, v38, v140
	v_add_f32_e32 v140, v140, v141
	v_add_f32_e32 v143, 1.0, v143
	v_pk_mul_f32 v[132:133], v[22:23], v[132:133]
	v_add_f32_e32 v132, v140, v132
	v_add_f32_e32 v215, v132, v133
	v_mul_f32_e32 v132, 0xbfb8aa3b, v215
	v_exp_f32_e32 v132, v132
	s_nop 0
	v_add_f32_e32 v145, 1.0, v132
	v_rcp_f32_e32 v133, v143
	s_nop 0
	v_mul_f32_e32 v142, v142, v133
	v_and_b32_e32 v133, 0xffff0000, v84
	v_and_b32_e32 v132, 0xffff0000, v72
	v_pk_mov_b32 v[140:141], v[138:139], v[132:133] op_sel:[1,0]
	v_pk_mul_f32 v[140:141], v[30:31], v[140:141]
	v_rcp_f32_e32 v143, v145
	s_nop 0
	v_mul_f32_e32 v143, v215, v143
	v_add_f32_e32 v140, v218, v140
	v_add_f32_e32 v140, v140, v141
	v_mul_f32_e32 v141, 0xbfb8aa3b, v140
	v_exp_f32_e32 v141, v141
	v_pk_mul_f32 v[138:139], v[170:171], v[138:139]
	v_pk_mul_f32 v[132:133], v[30:31], v[132:133]
	v_add_f32_e32 v138, v39, v138
	v_add_f32_e32 v141, 1.0, v141
	v_add_f32_e32 v138, v138, v139
	v_add_f32_e32 v132, v138, v132
	v_add_f32_e32 v133, v132, v133
	v_mul_f32_e32 v132, 0xbfb8aa3b, v133
	v_exp_f32_e32 v132, v132
	s_nop 0
	v_add_f32_e32 v145, 1.0, v132
	v_rcp_f32_e32 v132, v141
	s_nop 0
	v_mul_f32_e32 v132, v140, v132
	v_cvt_pk_bf16_f32 v132, v142, v132
	v_lshlrev_b32_e32 v138, 16, v73
	v_lshlrev_b32_e32 v139, 16, v85
	v_pk_mov_b32 v[140:141], v[136:137], v[138:139] op_sel:[1,0]
	v_pk_mul_f32 v[140:141], v[24:25], v[140:141]
	v_rcp_f32_e32 v142, v145
	s_nop 0
	v_mul_f32_e32 v142, v133, v142
	v_add_f32_e32 v140, v219, v140
	v_add_f32_e32 v140, v140, v141
	v_mul_f32_e32 v141, 0xbfb8aa3b, v140
	v_exp_f32_e32 v141, v141
	v_pk_mul_f32 v[136:137], v[160:161], v[136:137]
	v_add_f32_e32 v133, 1.0, v141
	v_add_f32_e32 v136, v40, v136
	v_add_f32_e32 v209, v136, v137
	v_pk_mul_f32 v[136:137], v[24:25], v[138:139]
	v_add_f32_e32 v136, v209, v136
	v_add_f32_e32 v209, v136, v137
	v_mul_f32_e32 v136, 0xbfb8aa3b, v209
	v_exp_f32_e32 v136, v136
	s_nop 0
	v_add_f32_e32 v141, 1.0, v136
	v_rcp_f32_e32 v137, v133
	s_nop 0
	v_mul_f32_e32 v133, v140, v137
	v_and_b32_e32 v137, 0xffff0000, v85
	v_and_b32_e32 v136, 0xffff0000, v73
	v_pk_mov_b32 v[138:139], v[134:135], v[136:137] op_sel:[1,0]
	v_pk_mul_f32 v[138:139], v[32:33], v[138:139]
	v_rcp_f32_e32 v140, v141
	s_nop 0
	v_mul_f32_e32 v140, v209, v140
	v_add_f32_e32 v138, v221, v138
	v_add_f32_e32 v138, v138, v139
	v_mul_f32_e32 v139, 0xbfb8aa3b, v138
	v_exp_f32_e32 v139, v139
	v_pk_mul_f32 v[134:135], v[162:163], v[134:135]
	v_add_f32_e32 v139, 1.0, v139
	v_add_f32_e32 v134, v41, v134
	v_add_f32_e32 v209, v134, v135
	v_pk_mul_f32 v[134:135], v[32:33], v[136:137]
	v_add_f32_e32 v134, v209, v134
	v_add_f32_e32 v134, v134, v135
	v_mul_f32_e32 v135, 0xbfb8aa3b, v134
	v_exp_f32_e32 v135, v135
	v_rcp_f32_e32 v136, v139
	s_nop 0
	v_mul_f32_e32 v136, v138, v136
	v_cvt_pk_bf16_f32 v133, v133, v136
	v_add_f32_e32 v135, 1.0, v135
	global_store_dwordx4 v[212:213], v[130:133], off
	s_nop 1
	v_rcp_f32_e32 v130, v135
	s_nop 0
	v_mul_f32_e32 v133, v134, v130
	v_lshl_add_u64 v[134:135], v[206:207], 0, v[198:199]
	v_cvt_pk_bf16_f32 v130, v210, v211
	v_cvt_pk_bf16_f32 v131, v208, v144
	v_cvt_pk_bf16_f32 v132, v143, v142
	v_cvt_pk_bf16_f32 v133, v140, v133
	global_store_dwordx4 v[134:135], v[130:133], off
	s_and_saveexec_b64 s[20:21], s[6:7]
	s_cbranch_execz .LBB0_745
	v_add_u32_e32 v130, s29, v233
	v_cmp_gt_i32_e32 vcc, s31, v130
	s_and_saveexec_b64 s[6:7], vcc
	s_cbranch_execz .LBB0_761
	v_add_u32_e32 v42, s28, v1
	v_add_u32_e32 v44, 0x4000, v42
	v_mov_b64_e32 v[42:43], s[10:11]
	v_mad_i64_i32 v[42:43], s[0:1], v44, s34, v[42:43]
	v_lshl_add_u64 v[42:43], v[146:147], 1, v[42:43]
	v_mov_b32_e32 v44, v151
	v_mov_b32_e32 v45, v151
	v_cmp_gt_i32_e32 vcc, s26, v130
	v_lshl_add_u64 v[70:71], v[42:43], 0, s[16:17]
	v_cmp_ne_u32_sdwa s[0:1], v130, v151 src0_sel:BYTE_0 src1_sel:DWORD
	v_mov_b32_e32 v42, 0
	v_mov_b32_e32 v43, v151
	v_mov_b64_e32 v[52:53], v[44:45]
	v_mov_b64_e32 v[48:49], v[44:45]
	s_and_b64 s[22:23], vcc, s[0:1]
	v_mov_b64_e32 v[50:51], v[42:43]
	v_mov_b64_e32 v[46:47], v[42:43]
	s_and_saveexec_b64 s[24:25], s[22:23]
	s_cbranch_execz .LBB0_758
	v_add_co_u32_e32 v46, vcc, 0xffff1000, v70
	s_nop 1
	v_addc_co_u32_e32 v47, vcc, -1, v71, vcc
	s_nop 1
	v_add_co_u32_e32 v50, vcc, 0xffff6000, v70
	s_nop 1
	v_addc_co_u32_e32 v51, vcc, -1, v71, vcc
	global_load_dwordx4 v[46:49], v[46:47], off offset:-1536
	s_nop 0
	global_load_dwordx4 v[50:53], v[50:51], off offset:-1024

.LBB0_760:
	s_or_b64 exec, exec, s[24:25]
	v_add_co_u32_e32 v54, vcc, 0x5000, v70
	s_nop 1
	v_addc_co_u32_e32 v55, vcc, 0, v71, vcc
	global_load_dwordx4 v[62:65], v[70:71], off
	global_load_dwordx4 v[66:69], v[54:55], off offset:512
	v_add_co_u32_e32 v54, vcc, 0xa000, v70
	s_nop 1
	v_addc_co_u32_e32 v55, vcc, 0, v71, vcc
	s_nop 1
	v_add_co_u32_e32 v56, vcc, 0xf000, v70
	s_nop 1
	v_addc_co_u32_e32 v57, vcc, 0, v71, vcc
	global_load_dwordx4 v[78:81], v[54:55], off offset:1024
	global_load_dwordx4 v[58:61], v[56:57], off offset:1536
	v_add_co_u32_e32 v54, vcc, 0x14000, v70
	s_nop 1
	v_addc_co_u32_e32 v55, vcc, 0, v71, vcc
	s_nop 1
	v_add_co_u32_e32 v56, vcc, 0x19000, v70
	s_nop 1
	v_addc_co_u32_e32 v57, vcc, 0, v71, vcc
	s_nop 1
	v_add_co_u32_e32 v72, vcc, 0x1e000, v70
	global_load_dwordx4 v[74:77], v[54:55], off offset:2048
	s_nop 0
	global_load_dwordx4 v[54:57], v[56:57], off offset:2560
	v_addc_co_u32_e32 v73, vcc, 0, v71, vcc
	s_nop 1
	v_add_co_u32_e32 v82, vcc, 0x23000, v70
	s_nop 1
	v_addc_co_u32_e32 v83, vcc, 0, v71, vcc
	global_load_dwordx4 v[70:73], v[72:73], off offset:3072
	s_nop 0
	global_load_dwordx4 v[82:85], v[82:83], off offset:3584

.LBB0_2205:
	s_cmp_lt_i32 s50, 12
	s_cselect_b64 s[0:1], -1, 0
	s_and_b64 s[8:9], s[0:1], s[4:5]
	s_andn2_b64 vcc, exec, s[8:9]
	s_cbranch_vccnz .LBB0_2231
	s_lshl_b32 s0, s48, 9
	s_mul_hi_i32 s0, s0, 0x2e8ba2e9
	s_lshr_b32 s1, s0, 31
	s_ashr_i32 s3, s0, 6
	s_add_i32 s3, s3, s1
	s_mul_i32 s0, s3, 0x160
	s_add_i32 s1, 0, 0x200f8
	v_cmp_gt_i32_e32 vcc, s0, v232
	s_add_i32 s0, 0, 0x20030
	v_mov_b32_e32 v2, s1
	v_mov_b32_e32 v6, s0
	s_waitcnt lgkmcnt(0)
	ds_read2_b64 v[2:5], v2 offset1:1
	ds_read_b64 v[6:7], v6
	s_waitcnt lgkmcnt(1)
	v_readfirstlane_b32 s6, v2
	v_readfirstlane_b32 s7, v3
	v_readfirstlane_b32 s4, v4
	v_readfirstlane_b32 s5, v5
	s_waitcnt lgkmcnt(0)
	v_readfirstlane_b32 s0, v6
	v_readfirstlane_b32 s1, v7
	s_and_saveexec_b64 s[10:11], vcc
	s_cbranch_execz .LBB0_2230
	s_mov_b32 s12, 0x176000
	v_cmp_gt_i32_e32 vcc, s12, v232
	s_and_b64 exec, exec, vcc
	s_cbranch_execz .LBB0_2230
	s_mov_b32 s12, 0x2e8ba2e9
	v_mul_hi_i32 v2, v232, s12
	v_lshrrev_b32_e32 v3, 31, v2
	v_ashrrev_i32_e32 v2, 6, v2
	v_add_u32_e32 v182, v2, v3
	v_mul_i32_i24_e32 v2, 0x160, v182
	v_sub_u32_e32 v2, v232, v2
	v_lshlrev_b32_e32 v74, 3, v2
	v_ashrrev_i32_e32 v75, 31, v74
	v_lshlrev_b64 v[18:19], 2, v[74:75]
	v_lshl_add_u64 v[20:21], s[6:7], 0, v[18:19]
	s_movk_i32 s6, 0x2000
	v_add_co_u32_e32 v22, vcc, s6, v20
	s_movk_i32 s6, 0x5000
	s_nop 0
	v_addc_co_u32_e32 v23, vcc, 0, v21, vcc
	flat_load_dwordx4 v[2:5], v[20:21]
	flat_load_dwordx4 v[6:9], v[20:21] offset:16
	v_add_co_u32_e32 v20, vcc, s6, v20
	s_add_u32 s12, s46, 0xb800000
	s_nop 0
	v_addc_co_u32_e32 v21, vcc, 0, v21, vcc
	v_lshl_add_u64 v[26:27], s[4:5], 0, v[18:19]
	s_addc_u32 s13, s47, 0
	flat_load_dwordx4 v[10:13], v[22:23] offset:3072
	flat_load_dwordx4 v[14:17], v[22:23] offset:3088
	flat_load_dwordx4 v[66:69], v[20:21] offset:2048
	flat_load_dwordx4 v[70:73], v[20:21] offset:2064
	s_nop 0
	flat_load_dwordx4 v[18:21], v[26:27]
	flat_load_dwordx4 v[22:25], v[26:27] offset:16
	v_lshlrev_b32_e32 v76, 2, v182
	s_movk_i32 s18, 0x2c00
	v_mov_b64_e32 v[26:27], s[12:13]
	v_mad_i64_i32 v[28:29], s[4:5], v76, s18, v[26:27]
	v_lshlrev_b64 v[122:123], 1, v[74:75]
	v_lshl_add_u64 v[30:31], v[28:29], 0, v[122:123]
	v_or_b32_e32 v28, 1, v76
	s_movk_i32 s19, 0x1000
	v_mad_i64_i32 v[28:29], s[4:5], v28, s18, v[26:27]
	v_add_co_u32_e32 v42, vcc, s19, v30
	v_lshl_add_u64 v[32:33], v[28:29], 0, v[122:123]
	v_or_b32_e32 v28, 2, v76
	v_addc_co_u32_e32 v43, vcc, 0, v31, vcc
	s_nop 0
	v_mad_i64_i32 v[28:29], s[4:5], v28, s18, v[26:27]
	v_add_co_u32_e32 v44, vcc, s19, v32
	v_lshl_add_u64 v[46:47], v[28:29], 0, v[122:123]
	v_or_b32_e32 v28, 3, v76
	v_addc_co_u32_e32 v45, vcc, 0, v33, vcc
	s_nop 0
	v_mad_i64_i32 v[26:27], s[4:5], v28, s18, v[26:27]
	v_add_co_u32_e32 v58, vcc, s19, v46
	v_lshl_add_u64 v[48:49], v[26:27], 0, v[122:123]
	s_nop 0
	v_addc_co_u32_e32 v59, vcc, 0, v47, vcc
	s_nop 1
	v_add_co_u32_e32 v60, vcc, s19, v48
	global_load_dwordx4 v[26:29], v[30:31], off
	global_load_dwordx4 v[34:37], v[32:33], off
	s_nop 0
	global_load_dwordx4 v[30:33], v[42:43], off offset:1536
	global_load_dwordx4 v[38:41], v[44:45], off offset:1536
	s_nop 0
	global_load_dwordx4 v[42:45], v[46:47], off
	global_load_dwordx4 v[50:53], v[48:49], off
	v_addc_co_u32_e32 v61, vcc, 0, v49, vcc
	global_load_dwordx4 v[46:49], v[58:59], off offset:1536
	global_load_dwordx4 v[54:57], v[60:61], off offset:1536
	s_mov_b32 s4, 0x15ffff
	v_mov_b32_e32 v180, 0x7fc
	v_cmp_lt_i32_e32 vcc, s4, v232
	v_mov_b32_e32 v62, 0
	v_mov_b32_e32 v63, 0
	v_cndmask_b32_e64 v58, v180, 4, vcc
	v_and_b32_e32 v58, v58, v76
	v_cmp_ne_u32_e32 vcc, 0, v58
	v_mov_b32_e32 v64, 0
	v_mov_b32_e32 v65, 0
	v_mov_b32_e32 v58, 0
	v_mov_b32_e32 v59, 0
	v_mov_b32_e32 v60, 0
	v_mov_b32_e32 v61, 0
	s_and_saveexec_b64 s[4:5], vcc
	s_cbranch_execz .LBB0_2210
	v_add_u32_e32 v60, -2, v76
	v_mov_b64_e32 v[58:59], s[12:13]
	v_mad_i64_i32 v[60:61], s[6:7], v60, s18, v[58:59]
	v_lshl_add_u64 v[78:79], v[60:61], 0, v[122:123]
	v_add_u32_e32 v60, -1, v76
	v_mad_i64_i32 v[58:59], s[6:7], v60, s18, v[58:59]
	v_lshl_add_u64 v[80:81], v[58:59], 0, v[122:123]
	global_load_dwordx4 v[62:65], v[78:79], off
	global_load_dwordx4 v[58:61], v[80:81], off

.LBB0_2211:
	s_or_b64 exec, exec, s[4:5]
	v_fma_f32 v156, v9, v117, v25
	s_waitcnt vmcnt(11)
	v_lshlrev_b32_e32 v117, 16, v70
	v_mov_b32_e32 v144, v117
	v_fma_f32 v110, v2, v118, v18
	v_fma_f32 v153, v6, v114, v22
	v_fma_f32 v154, v7, v115, v23
	v_pk_mul_f32 v[114:115], v[136:137], v[144:145]
	v_fma_f32 v140, v3, v119, v19
	v_add_f32_e32 v110, v115, v110
	v_add_f32_e32 v110, v114, v110
	v_mul_f32_e32 v114, 0xbfb8aa3b, v110
	v_exp_f32_e32 v114, v114
	v_fma_f32 v155, v8, v116, v24
	s_waitcnt vmcnt(9)
	v_lshlrev_b32_e32 v116, 16, v78
	v_fma_f32 v145, v2, v145, v18
	v_add_f32_e32 v118, 1.0, v114
	v_lshlrev_b32_e32 v106, 16, v66
	v_pk_mul_f32 v[114:115], v[136:137], v[116:117]
	v_add_f32_e32 v115, v115, v145
	v_add_f32_e32 v114, v114, v115
	v_mul_f32_e32 v115, 0xbfb8aa3b, v114
	v_exp_f32_e32 v115, v115
	s_nop 0
	v_add_f32_e32 v145, 1.0, v115
	v_rcp_f32_e32 v119, v118
	s_nop 0
	v_mul_f32_e32 v110, v110, v119
	v_mul_f32_e32 v106, v110, v106
	v_and_b32_e32 v115, 0xffff0000, v70
	v_mov_b32_e32 v110, v115
	v_pk_mul_f32 v[118:119], v[10:11], v[110:111]
	v_fma_f32 v152, v5, v121, v21
	v_add_f32_e32 v110, v119, v140
	v_add_f32_e32 v118, v118, v110
	v_mul_f32_e32 v110, 0xbfb8aa3b, v118
	v_exp_f32_e32 v110, v110
	v_rcp_f32_e32 v119, v145
	s_nop 0
	v_mul_f32_e32 v114, v114, v119
	s_waitcnt vmcnt(8)
	v_lshlrev_b32_e32 v121, 16, v74
	v_add_f32_e32 v119, 1.0, v110
	v_mul_f32_e32 v161, v114, v121
	v_and_b32_e32 v114, 0xffff0000, v78
	v_fma_f32 v121, v3, v111, v19
	v_pk_mul_f32 v[110:111], v[10:11], v[114:115]
	v_and_b32_e32 v108, 0xffff0000, v66
	v_add_f32_e32 v111, v111, v121
	v_add_f32_e32 v111, v110, v111
	v_mul_f32_e32 v110, 0xbfb8aa3b, v111
	v_exp_f32_e32 v110, v110
	v_fma_f32 v120, v4, v120, v20
	v_add_f32_e32 v145, 1.0, v110
	v_rcp_f32_e32 v121, v119
	s_nop 0
	v_mul_f32_e32 v110, v118, v121
	v_mul_f32_e32 v108, v110, v108
	v_cvt_pk_bf16_f32 v110, v106, v108
	v_lshlrev_b32_e32 v121, 16, v71
	v_mov_b32_e32 v140, v121
	v_pk_mul_f32 v[118:119], v[134:135], v[140:141]
	v_add_f32_e32 v119, v119, v120
	v_add_f32_e32 v140, v118, v119
	v_mul_f32_e32 v118, 0xbfb8aa3b, v140
	v_exp_f32_e32 v118, v118
	v_rcp_f32_e32 v106, v145
	s_nop 0
	v_mul_f32_e32 v106, v111, v106
	v_mad_i64_i32 v[146:147], s[0:1], v138, s25, v[126:127]
	v_add_f32_e32 v108, 1.0, v118
	v_and_b32_e32 v138, 0xffff0000, v74
	v_lshlrev_b32_e32 v120, 16, v79
	v_mul_f32_e32 v163, v106, v138
	v_fma_f32 v106, v4, v141, v20
	v_pk_mul_f32 v[118:119], v[134:135], v[120:121]
	v_add_f32_e32 v106, v119, v106
	v_add_f32_e32 v106, v118, v106
	v_mul_f32_e32 v118, 0xbfb8aa3b, v106
	v_exp_f32_e32 v118, v118
	s_nop 0
	v_add_f32_e32 v118, 1.0, v118
	v_rcp_f32_e32 v111, v108
	s_nop 0
	v_mul_f32_e32 v108, v140, v111
	v_lshlrev_b32_e32 v112, 16, v67
	v_mul_f32_e32 v108, v108, v112
	v_and_b32_e32 v119, 0xffff0000, v71
	v_mov_b32_e32 v112, v119
	v_pk_mul_f32 v[140:141], v[12:13], v[112:113]
	v_add_f32_e32 v112, v141, v152
	v_add_f32_e32 v140, v140, v112
	v_mul_f32_e32 v112, 0xbfb8aa3b, v140
	v_exp_f32_e32 v112, v112
	v_rcp_f32_e32 v111, v118
	s_nop 0
	v_mul_f32_e32 v106, v106, v111
	v_lshlrev_b32_e32 v157, 16, v75
	v_mul_f32_e32 v152, v106, v157
	v_add_f32_e32 v111, 1.0, v112
	v_and_b32_e32 v118, 0xffff0000, v79
	v_fma_f32 v106, v5, v113, v21
	v_pk_mul_f32 v[112:113], v[12:13], v[118:119]
	v_and_b32_e32 v142, 0xffff0000, v67
	v_add_f32_e32 v106, v113, v106
	v_add_f32_e32 v106, v112, v106
	v_mul_f32_e32 v112, 0xbfb8aa3b, v106
	v_exp_f32_e32 v112, v112
	v_rcp_f32_e32 v113, v111
	s_nop 0
	v_mul_f32_e32 v111, v140, v113
	v_add_f32_e32 v145, 1.0, v112
	v_mul_f32_e32 v111, v111, v142
	v_cvt_pk_bf16_f32 v111, v108, v111
	v_lshlrev_b32_e32 v141, 16, v72
	v_mov_b32_e32 v138, v141
	v_pk_mul_f32 v[112:113], v[132:133], v[138:139]
	v_add_f32_e32 v113, v113, v153
	v_add_f32_e32 v138, v112, v113
	v_mul_f32_e32 v112, 0xbfb8aa3b, v138
	v_exp_f32_e32 v112, v112
	v_rcp_f32_e32 v108, v145
	s_nop 0
	v_mul_f32_e32 v106, v106, v108
	v_and_b32_e32 v158, 0xffff0000, v75
	v_lshlrev_b32_e32 v140, 16, v80
	v_add_f32_e32 v108, 1.0, v112
	v_mul_f32_e32 v153, v106, v158
	v_fma_f32 v106, v6, v139, v22
	v_pk_mul_f32 v[112:113], v[132:133], v[140:141]
	v_add_f32_e32 v106, v113, v106
	v_add_f32_e32 v158, v112, v106
	v_mul_f32_e32 v106, 0xbfb8aa3b, v158
	v_exp_f32_e32 v106, v106
	s_nop 0
	v_add_f32_e32 v142, 1.0, v106
	v_rcp_f32_e32 v112, v108
	s_nop 0
	v_mul_f32_e32 v108, v138, v112
	v_and_b32_e32 v139, 0xffff0000, v72
	v_mov_b32_e32 v106, v139
	v_pk_mul_f32 v[112:113], v[14:15], v[106:107]
	v_lshlrev_b32_e32 v148, 16, v68
	v_add_f32_e32 v106, v113, v154
	v_add_f32_e32 v112, v112, v106
	v_mul_f32_e32 v106, 0xbfb8aa3b, v112
	v_exp_f32_e32 v106, v106
	v_rcp_f32_e32 v113, v142
	s_nop 0
	v_mul_f32_e32 v113, v158, v113
	v_mul_f32_e32 v108, v108, v148
	v_add_f32_e32 v142, 1.0, v106
	v_lshlrev_b32_e32 v144, 16, v76
	v_mul_f32_e32 v154, v113, v144
	v_and_b32_e32 v138, 0xffff0000, v80
	v_fma_f32 v113, v7, v107, v23
	v_pk_mul_f32 v[106:107], v[14:15], v[138:139]
	v_and_b32_e32 v149, 0xffff0000, v68
	v_add_f32_e32 v107, v107, v113
	v_add_f32_e32 v113, v106, v107
	v_mul_f32_e32 v106, 0xbfb8aa3b, v113
	v_exp_f32_e32 v106, v106
	v_rcp_f32_e32 v107, v142
	s_nop 0
	v_mul_f32_e32 v107, v112, v107
	v_add_f32_e32 v144, 1.0, v106
	v_mul_f32_e32 v107, v107, v149
	v_cvt_pk_bf16_f32 v112, v108, v107
	v_lshlrev_b32_e32 v145, 16, v73
	v_mov_b32_e32 v142, v145
	v_pk_mul_f32 v[106:107], v[130:131], v[142:143]
	v_and_b32_e32 v159, 0xffff0000, v76
	v_add_f32_e32 v107, v107, v155
	v_add_f32_e32 v142, v106, v107
	v_mul_f32_e32 v106, 0xbfb8aa3b, v142
	v_exp_f32_e32 v106, v106
	v_rcp_f32_e32 v107, v144
	s_nop 0
	v_mul_f32_e32 v107, v113, v107
	v_lshlrev_b32_e32 v144, 16, v81
	v_add_f32_e32 v108, 1.0, v106
	v_mul_f32_e32 v149, v107, v159
	v_fma_f32 v143, v8, v143, v24
	v_pk_mul_f32 v[106:107], v[130:131], v[144:145]
	v_add_f32_e32 v107, v107, v143
	v_add_f32_e32 v158, v106, v107
	v_mul_f32_e32 v106, 0xbfb8aa3b, v158
	v_exp_f32_e32 v106, v106
	s_nop 0
	v_add_f32_e32 v113, 1.0, v106
	v_lshlrev_b32_e32 v150, 16, v69
	v_rcp_f32_e32 v107, v108
	s_nop 0
	v_mul_f32_e32 v107, v142, v107
	v_mul_f32_e32 v148, v107, v150
	v_and_b32_e32 v143, 0xffff0000, v73
	v_mov_b32_e32 v108, v143
	v_pk_mul_f32 v[106:107], v[16:17], v[108:109]
	v_lshlrev_b32_e32 v160, 16, v77
	v_add_f32_e32 v107, v107, v156
	v_add_f32_e32 v108, v106, v107
	v_mul_f32_e32 v106, 0xbfb8aa3b, v108
	v_exp_f32_e32 v106, v106
	v_rcp_f32_e32 v107, v113
	s_nop 0
	v_mul_f32_e32 v107, v158, v107
	v_mul_f32_e32 v155, v107, v160
	v_add_f32_e32 v113, 1.0, v106
	v_and_b32_e32 v142, 0xffff0000, v81
	v_fma_f32 v109, v9, v109, v25
	v_and_b32_e32 v151, 0xffff0000, v69
	v_pk_mul_f32 v[106:107], v[16:17], v[142:143]
	v_and_b32_e32 v162, 0xffff0000, v77
	v_add_f32_e32 v107, v107, v109
	v_add_f32_e32 v106, v106, v107
	v_mul_f32_e32 v107, 0xbfb8aa3b, v106
	v_exp_f32_e32 v107, v107
	v_rcp_f32_e32 v109, v113
	s_nop 0
	v_mul_f32_e32 v108, v108, v109
	v_mul_f32_e32 v108, v108, v151
	v_add_f32_e32 v107, 1.0, v107
	v_cvt_pk_bf16_f32 v113, v148, v108
	global_store_dwordx4 v[146:147], v[110:113], off
	v_fma_f32 v117, v2, v117, v18
	v_rcp_f32_e32 v108, v107
	s_nop 0
	v_mul_f32_e32 v106, v106, v108
	v_add_u32_e32 v110, 0x4001, v183
	v_mul_f32_e32 v109, v106, v162
	v_cvt_pk_bf16_f32 v106, v161, v163
	v_mad_i64_i32 v[110:111], s[0:1], v110, s25, v[126:127]
	v_cvt_pk_bf16_f32 v107, v152, v153
	v_cvt_pk_bf16_f32 v108, v154, v149
	v_cvt_pk_bf16_f32 v109, v155, v109
	global_store_dwordx4 v[110:111], v[106:109], off
	s_waitcnt vmcnt(8)
	v_lshlrev_b32_e32 v112, 16, v82
	v_fma_f32 v152, v3, v115, v19
	v_add_u32_e32 v106, 0x4002, v183
	v_mad_i64_i32 v[110:111], s[0:1], v106, s25, v[126:127]
	v_lshlrev_b32_e32 v107, 16, v86
	s_waitcnt vmcnt(7)
	v_lshlrev_b32_e32 v106, 16, v94
	v_pk_mov_b32 v[108:109], v[106:107], v[116:117] op_sel:[1,0]
	v_fma_f32 v116, v2, v116, v18
	v_pk_mul_f32 v[108:109], v[136:137], v[108:109]
	v_pk_mul_f32 v[106:107], v[136:137], v[106:107]
	v_add_f32_e32 v109, v109, v117
	v_add_f32_e32 v108, v108, v109
	v_mul_f32_e32 v109, 0xbfb8aa3b, v108
	v_exp_f32_e32 v109, v109
	v_add_f32_e32 v107, v107, v116
	v_add_f32_e32 v116, v106, v107
	v_mul_f32_e32 v106, 0xbfb8aa3b, v116
	v_add_f32_e32 v109, 1.0, v109
	v_exp_f32_e32 v106, v106
	s_waitcnt vmcnt(6)
	v_lshlrev_b32_e32 v156, 16, v90
	v_and_b32_e32 v113, 0xffff0000, v82
	v_add_f32_e32 v161, 1.0, v106
	v_rcp_f32_e32 v106, v109
	s_nop 0
	v_mul_f32_e32 v106, v108, v106
	v_mul_f32_e32 v112, v106, v112
	v_and_b32_e32 v107, 0xffff0000, v86
	v_and_b32_e32 v106, 0xffff0000, v94
	v_pk_mov_b32 v[108:109], v[106:107], v[114:115] op_sel:[1,0]
	v_pk_mul_f32 v[108:109], v[10:11], v[108:109]
	v_fma_f32 v114, v3, v114, v19
	v_add_f32_e32 v109, v109, v152
	v_add_f32_e32 v108, v108, v109
	v_mul_f32_e32 v109, 0xbfb8aa3b, v108
	v_exp_f32_e32 v109, v109
	v_pk_mul_f32 v[106:107], v[10:11], v[106:107]
	v_add_f32_e32 v107, v107, v114
	v_add_f32_e32 v109, 1.0, v109
	v_rcp_f32_e32 v115, v161
	s_nop 0
	v_mul_f32_e32 v115, v116, v115
	v_add_f32_e32 v107, v106, v107
	v_mul_f32_e32 v116, v115, v156
	v_mul_f32_e32 v106, 0xbfb8aa3b, v107
	v_exp_f32_e32 v106, v106
	s_nop 0
	v_add_f32_e32 v115, 1.0, v106
	v_rcp_f32_e32 v114, v109
	s_nop 0
	v_mul_f32_e32 v106, v108, v114
	v_fma_f32 v121, v4, v121, v20
	v_mul_f32_e32 v106, v106, v113
	v_lshlrev_b32_e32 v109, 16, v87
	v_lshlrev_b32_e32 v108, 16, v95
	v_cvt_pk_bf16_f32 v106, v112, v106
	v_pk_mov_b32 v[112:113], v[108:109], v[120:121] op_sel:[1,0]
	v_pk_mul_f32 v[112:113], v[134:135], v[112:113]
	v_add_f32_e32 v113, v113, v121
	v_add_f32_e32 v112, v112, v113
	v_mul_f32_e32 v113, 0xbfb8aa3b, v112
	v_exp_f32_e32 v113, v113
	v_and_b32_e32 v157, 0xffff0000, v90
	v_rcp_f32_e32 v114, v115
	s_nop 0
	v_mul_f32_e32 v107, v107, v114
	v_mul_f32_e32 v156, v107, v157
	v_add_f32_e32 v113, 1.0, v113
	v_fma_f32 v107, v4, v120, v20
	v_pk_mul_f32 v[108:109], v[134:135], v[108:109]
	v_lshlrev_b32_e32 v146, 16, v83
	v_add_f32_e32 v107, v109, v107
	v_add_f32_e32 v107, v108, v107
	v_mul_f32_e32 v108, 0xbfb8aa3b, v107
	v_exp_f32_e32 v108, v108
	s_nop 0
	v_add_f32_e32 v114, 1.0, v108
	v_rcp_f32_e32 v108, v113
	s_nop 0
	v_mul_f32_e32 v108, v112, v108
	v_mul_f32_e32 v115, v108, v146
	v_and_b32_e32 v109, 0xffff0000, v87
	v_and_b32_e32 v108, 0xffff0000, v95
	v_pk_mov_b32 v[112:113], v[108:109], v[118:119] op_sel:[1,0]
	v_fma_f32 v153, v5, v119, v21
	v_pk_mul_f32 v[112:113], v[12:13], v[112:113]
	v_add_f32_e32 v113, v113, v153
	v_add_f32_e32 v112, v112, v113
	v_mul_f32_e32 v113, 0xbfb8aa3b, v112
	v_exp_f32_e32 v113, v113
	v_rcp_f32_e32 v119, v114
	s_nop 0
	v_mul_f32_e32 v107, v107, v119
	v_lshlrev_b32_e32 v158, 16, v91
	v_add_f32_e32 v113, 1.0, v113
	v_mul_f32_e32 v119, v107, v158
	v_fma_f32 v107, v5, v118, v21
	v_pk_mul_f32 v[108:109], v[12:13], v[108:109]
	v_add_f32_e32 v107, v109, v107
	v_add_f32_e32 v146, v108, v107
	v_mul_f32_e32 v107, 0xbfb8aa3b, v146
	v_exp_f32_e32 v107, v107
	v_and_b32_e32 v147, 0xffff0000, v83
	v_add_f32_e32 v114, 1.0, v107
	v_rcp_f32_e32 v108, v113
	s_nop 0
	v_mul_f32_e32 v107, v112, v108
	v_mul_f32_e32 v107, v107, v147
	v_cvt_pk_bf16_f32 v107, v115, v107
	v_fma_f32 v141, v6, v141, v22
	v_lshlrev_b32_e32 v109, 16, v88
	v_lshlrev_b32_e32 v108, 16, v96
	v_pk_mov_b32 v[112:113], v[108:109], v[140:141] op_sel:[1,0]
	v_pk_mul_f32 v[112:113], v[132:133], v[112:113]
	v_add_f32_e32 v113, v113, v141
	v_add_f32_e32 v112, v112, v113
	v_mul_f32_e32 v113, 0xbfb8aa3b, v112
	v_exp_f32_e32 v113, v113
	v_and_b32_e32 v117, 0xffff0000, v91
	v_rcp_f32_e32 v115, v114
	s_nop 0
	v_mul_f32_e32 v114, v146, v115
	v_mul_f32_e32 v117, v114, v117
	v_add_f32_e32 v113, 1.0, v113
	v_fma_f32 v114, v6, v140, v22
	v_pk_mul_f32 v[108:109], v[132:133], v[108:109]
	v_lshlrev_b32_e32 v148, 16, v84
	v_add_f32_e32 v109, v109, v114
	v_add_f32_e32 v114, v108, v109
	v_mul_f32_e32 v108, 0xbfb8aa3b, v114
	v_exp_f32_e32 v108, v108
	s_nop 0
	v_add_f32_e32 v115, 1.0, v108
	v_rcp_f32_e32 v108, v113
	s_nop 0
	v_mul_f32_e32 v108, v112, v108
	v_mul_f32_e32 v120, v108, v148
	v_and_b32_e32 v109, 0xffff0000, v88
	v_and_b32_e32 v108, 0xffff0000, v96
	v_pk_mov_b32 v[112:113], v[108:109], v[138:139] op_sel:[1,0]
	v_fma_f32 v154, v7, v139, v23
	v_pk_mul_f32 v[112:113], v[14:15], v[112:113]
	v_add_f32_e32 v113, v113, v154
	v_add_f32_e32 v112, v112, v113
	v_mul_f32_e32 v113, 0xbfb8aa3b, v112
	v_exp_f32_e32 v113, v113
	v_lshlrev_b32_e32 v159, 16, v92
	v_rcp_f32_e32 v118, v115
	s_nop 0
	v_mul_f32_e32 v114, v114, v118
	v_add_f32_e32 v113, 1.0, v113
	v_mul_f32_e32 v118, v114, v159
	v_fma_f32 v114, v7, v138, v23
	v_pk_mul_f32 v[108:109], v[14:15], v[108:109]
	v_add_f32_e32 v109, v109, v114
	v_add_f32_e32 v109, v108, v109
	v_mul_f32_e32 v108, 0xbfb8aa3b, v109
	v_exp_f32_e32 v108, v108
	s_nop 0
	v_add_f32_e32 v121, 1.0, v108
	v_and_b32_e32 v149, 0xffff0000, v84
	v_rcp_f32_e32 v114, v113
	s_nop 0
	v_mul_f32_e32 v108, v112, v114
	v_mul_f32_e32 v108, v108, v149
	v_cvt_pk_bf16_f32 v108, v120, v108
	v_fma_f32 v145, v8, v145, v24
	v_lshlrev_b32_e32 v113, 16, v89
	v_lshlrev_b32_e32 v112, 16, v97
	v_pk_mov_b32 v[114:115], v[112:113], v[144:145] op_sel:[1,0]
	v_pk_mul_f32 v[114:115], v[130:131], v[114:115]
	v_add_f32_e32 v115, v115, v145
	v_add_f32_e32 v114, v114, v115
	v_mul_f32_e32 v115, 0xbfb8aa3b, v114
	v_exp_f32_e32 v115, v115
	v_and_b32_e32 v160, 0xffff0000, v92
	v_rcp_f32_e32 v120, v121
	s_nop 0
	v_mul_f32_e32 v109, v109, v120
	v_mul_f32_e32 v120, v109, v160
	v_add_f32_e32 v115, 1.0, v115
	v_fma_f32 v109, v8, v144, v24
	v_pk_mul_f32 v[112:113], v[130:131], v[112:113]
	v_lshlrev_b32_e32 v150, 16, v85
	v_add_f32_e32 v109, v113, v109
	v_add_f32_e32 v109, v112, v109
	v_mul_f32_e32 v112, 0xbfb8aa3b, v109
	v_exp_f32_e32 v112, v112
	s_nop 0
	v_add_f32_e32 v121, 1.0, v112
	v_rcp_f32_e32 v112, v115
	s_nop 0
	v_mul_f32_e32 v112, v114, v112
	v_mul_f32_e32 v139, v112, v150
	v_and_b32_e32 v113, 0xffff0000, v89
	v_and_b32_e32 v112, 0xffff0000, v97
	v_pk_mov_b32 v[114:115], v[112:113], v[142:143] op_sel:[1,0]
	v_fma_f32 v155, v9, v143, v25
	v_pk_mul_f32 v[114:115], v[16:17], v[114:115]
	v_add_f32_e32 v115, v115, v155
	v_add_f32_e32 v114, v114, v115
	v_mul_f32_e32 v115, 0xbfb8aa3b, v114
	v_exp_f32_e32 v115, v115
	v_lshlrev_b32_e32 v163, 16, v93
	v_rcp_f32_e32 v138, v121
	s_nop 0
	v_mul_f32_e32 v109, v109, v138
	v_add_f32_e32 v115, 1.0, v115
	v_mul_f32_e32 v121, v109, v163
	v_fma_f32 v109, v9, v142, v25
	v_pk_mul_f32 v[112:113], v[16:17], v[112:113]
	v_add_f32_e32 v109, v113, v109
	v_add_f32_e32 v112, v112, v109
	v_mul_f32_e32 v109, 0xbfb8aa3b, v112
	v_exp_f32_e32 v109, v109
	v_rcp_f32_e32 v113, v115
	s_nop 0
	v_mul_f32_e32 v113, v114, v113
	v_add_f32_e32 v114, 1.0, v109
	v_and_b32_e32 v151, 0xffff0000, v85
	v_mul_f32_e32 v109, v113, v151
	v_cvt_pk_bf16_f32 v109, v139, v109
	global_store_dwordx4 v[110:111], v[106:109], off
	v_add_u32_e32 v182, s3, v184
	v_and_b32_e32 v164, 0xffff0000, v93
	v_rcp_f32_e32 v106, v114
	s_nop 0
	v_mul_f32_e32 v106, v112, v106
	v_add_u32_e32 v110, 0x4003, v183
	v_cmp_lt_i32_e32 vcc, s26, v182
	v_mul_f32_e32 v109, v106, v164
	v_mad_i64_i32 v[110:111], s[0:1], v110, s25, v[126:127]
	v_add_u32_e32 v181, s20, v181
	s_orn2_b64 s[16:17], vcc, exec
	v_cvt_pk_bf16_f32 v106, v116, v156
	v_cvt_pk_bf16_f32 v107, v119, v117
	v_cvt_pk_bf16_f32 v108, v118, v120
	v_cvt_pk_bf16_f32 v109, v121, v109
	global_store_dwordx4 v[110:111], v[106:109], off

.LBB0_2213:
	v_add_u32_e32 v184, s3, v182
	v_cmp_gt_i32_e64 s[4:5], s23, v184
	v_add_u32_e32 v183, s22, v181
	s_and_saveexec_b64 s[6:7], s[4:5]
	s_cbranch_execz .LBB0_2217
	s_waitcnt vmcnt(4)
	v_add_u32_e32 v102, 0x4000, v183
	v_mov_b64_e32 v[90:91], s[12:13]
	v_mad_i64_i32 v[66:67], s[0:1], v102, s18, v[90:91]
	v_lshl_add_u64 v[74:75], v[66:67], 0, v[122:123]
	v_add_co_u32_e32 v76, vcc, 0x1000, v74
	v_mov_b32_e32 v105, 0
	s_nop 0
	v_addc_co_u32_e32 v77, vcc, 0, v75, vcc
	global_load_dwordx4 v[70:73], v[74:75], off
	global_load_dwordx4 v[66:69], v[76:77], off offset:1536
	v_add_u32_e32 v74, 0x4001, v183
	v_mad_i64_i32 v[74:75], s[0:1], v74, s18, v[90:91]
	v_lshl_add_u64 v[82:83], v[74:75], 0, v[122:123]
	v_add_co_u32_e32 v84, vcc, 0x1000, v82
	v_mov_b32_e32 v104, 0
	s_nop 0
	v_addc_co_u32_e32 v85, vcc, 0, v83, vcc
	global_load_dwordx4 v[78:81], v[82:83], off
	global_load_dwordx4 v[74:77], v[84:85], off offset:1536
	v_add_u32_e32 v82, 0x4002, v183
	v_mad_i64_i32 v[82:83], s[0:1], v82, s18, v[90:91]
	v_lshl_add_u64 v[92:93], v[82:83], 0, v[122:123]
	v_add_co_u32_e32 v94, vcc, 0x1000, v92
	v_mov_b32_e32 v103, 0
	s_nop 0
	v_addc_co_u32_e32 v95, vcc, 0, v93, vcc
	global_load_dwordx4 v[86:89], v[92:93], off
	global_load_dwordx4 v[82:85], v[94:95], off offset:1536
	v_add_u32_e32 v92, 0x4003, v183
	v_mad_i64_i32 v[90:91], s[0:1], v92, s18, v[90:91]
	v_lshl_add_u64 v[98:99], v[90:91], 0, v[122:123]
	v_add_co_u32_e32 v100, vcc, 0x1000, v98
	s_nop 1
	v_addc_co_u32_e32 v101, vcc, 0, v99, vcc
	global_load_dwordx4 v[94:97], v[98:99], off
	global_load_dwordx4 v[90:93], v[100:101], off offset:1536
	v_cmp_lt_i32_e32 vcc, s24, v184
	v_mov_b32_e32 v101, 0
	v_mov_b32_e32 v100, 0
	v_cndmask_b32_e64 v98, v180, 4, vcc
	v_and_b32_e32 v98, v98, v102
	v_cmp_ne_u32_e32 vcc, 0, v98
	v_mov_b32_e32 v99, 0
	v_mov_b32_e32 v98, 0
	v_mov_b32_e32 v102, 0
	s_and_saveexec_b64 s[16:17], vcc
	s_cbranch_execz .LBB0_2216
	v_add_u32_e32 v98, 0x3ffe, v183
	v_add_u32_e32 v100, 0x3fff, v183
	v_mad_i64_i32 v[98:99], s[0:1], v98, s18, v[124:125]
	s_nop 1
	v_mad_i64_i32 v[102:103], s[0:1], v100, s18, v[124:125]
	global_load_dwordx4 v[98:101], v[98:99], off
	s_nop 0
	global_load_dwordx4 v[102:105], v[102:103], off

.LBB0_2221:
	s_or_b64 exec, exec, s[6:7]
	v_lshlrev_b32_e32 v171, 16, v26
	v_mov_b32_e32 v176, v171
	v_fma_f32 v110, v2, v118, v18
	v_fma_f32 v190, v8, v116, v24
	v_fma_f32 v191, v9, v117, v25
	v_pk_mul_f32 v[116:117], v[136:137], v[176:177]
	v_lshlrev_b32_e32 v170, 16, v34
	v_add_f32_e32 v110, v117, v110
	v_add_f32_e32 v110, v116, v110
	v_mul_f32_e32 v116, 0xbfb8aa3b, v110
	v_exp_f32_e32 v116, v116
	v_fma_f32 v177, v2, v177, v18
	v_lshlrev_b32_e32 v106, 16, v30
	v_and_b32_e32 v165, 0xffff0000, v26
	v_add_f32_e32 v174, 1.0, v116
	v_fma_f32 v118, v3, v119, v19
	v_pk_mul_f32 v[116:117], v[136:137], v[170:171]
	v_add_f32_e32 v117, v117, v177
	v_add_f32_e32 v177, v116, v117
	v_mul_f32_e32 v116, 0xbfb8aa3b, v177
	v_exp_f32_e32 v116, v116
	s_nop 0
	v_add_f32_e32 v196, 1.0, v116
	v_rcp_f32_e32 v116, v174
	s_nop 0
	v_mul_f32_e32 v110, v110, v116
	v_mul_f32_e32 v106, v110, v106
	v_mov_b32_e32 v110, v165
	v_pk_mul_f32 v[116:117], v[10:11], v[110:111]
	v_fma_f32 v119, v4, v120, v20
	v_add_f32_e32 v110, v117, v118
	v_add_f32_e32 v116, v116, v110
	v_mul_f32_e32 v110, 0xbfb8aa3b, v116
	v_exp_f32_e32 v110, v110
	v_fma_f32 v120, v5, v121, v21
	v_add_f32_e32 v118, 1.0, v110
	v_fma_f32 v121, v6, v114, v22
	v_fma_f32 v189, v7, v115, v23
	v_mad_i64_i32 v[114:115], s[0:1], v168, s25, v[126:127]
	v_lshlrev_b32_e32 v168, 16, v38
	v_rcp_f32_e32 v117, v196
	s_nop 0
	v_mul_f32_e32 v110, v177, v117
	v_mul_f32_e32 v177, v110, v168
	v_and_b32_e32 v164, 0xffff0000, v34
	v_fma_f32 v117, v3, v111, v19
	v_pk_mul_f32 v[110:111], v[10:11], v[164:165]
	v_and_b32_e32 v108, 0xffff0000, v30
	v_add_f32_e32 v111, v111, v117
	v_add_f32_e32 v111, v110, v111
	v_mul_f32_e32 v110, 0xbfb8aa3b, v111
	v_exp_f32_e32 v110, v110
	v_lshlrev_b32_e32 v161, 16, v27
	v_add_f32_e32 v168, 1.0, v110
	v_rcp_f32_e32 v117, v118
	s_nop 0
	v_mul_f32_e32 v110, v116, v117
	v_mul_f32_e32 v108, v110, v108
	v_cvt_pk_bf16_f32 v110, v106, v108
	v_mov_b32_e32 v174, v161
	v_pk_mul_f32 v[116:117], v[134:135], v[174:175]
	v_add_f32_e32 v117, v117, v119
	v_add_f32_e32 v118, v116, v117
	v_mul_f32_e32 v116, 0xbfb8aa3b, v118
	v_exp_f32_e32 v116, v116
	v_lshlrev_b32_e32 v160, 16, v35
	v_and_b32_e32 v192, 0xffff0000, v38
	v_add_f32_e32 v108, 1.0, v116
	v_rcp_f32_e32 v106, v168
	s_nop 0
	v_mul_f32_e32 v106, v111, v106
	v_mul_f32_e32 v192, v106, v192
	v_fma_f32 v106, v4, v175, v20
	v_pk_mul_f32 v[116:117], v[134:135], v[160:161]
	v_add_f32_e32 v106, v117, v106
	v_add_f32_e32 v106, v116, v106
	v_mul_f32_e32 v116, 0xbfb8aa3b, v106
	v_exp_f32_e32 v116, v116
	s_nop 0
	v_add_f32_e32 v119, 1.0, v116
	v_rcp_f32_e32 v111, v108
	s_nop 0
	v_mul_f32_e32 v108, v118, v111
	v_lshlrev_b32_e32 v112, 16, v31
	v_and_b32_e32 v157, 0xffff0000, v27
	v_mul_f32_e32 v108, v108, v112
	v_mov_b32_e32 v112, v157
	v_pk_mul_f32 v[116:117], v[12:13], v[112:113]
	v_add_f32_e32 v112, v117, v120
	v_add_f32_e32 v116, v116, v112
	v_mul_f32_e32 v112, 0xbfb8aa3b, v116
	v_exp_f32_e32 v112, v112
	v_rcp_f32_e32 v111, v119
	s_nop 0
	v_mul_f32_e32 v106, v106, v111
	v_and_b32_e32 v156, 0xffff0000, v35
	v_add_f32_e32 v117, 1.0, v112
	v_lshlrev_b32_e32 v193, 16, v39
	v_mul_f32_e32 v119, v106, v193
	v_fma_f32 v106, v5, v113, v21
	v_pk_mul_f32 v[112:113], v[12:13], v[156:157]
	v_add_f32_e32 v106, v113, v106
	v_add_f32_e32 v106, v112, v106
	v_mul_f32_e32 v112, 0xbfb8aa3b, v106
	v_exp_f32_e32 v112, v112
	v_and_b32_e32 v172, 0xffff0000, v31
	v_rcp_f32_e32 v111, v117
	s_nop 0
	v_mul_f32_e32 v111, v116, v111
	v_add_f32_e32 v118, 1.0, v112
	v_mul_f32_e32 v111, v111, v172
	v_cvt_pk_bf16_f32 v111, v108, v111
	v_lshlrev_b32_e32 v153, 16, v28
	v_mov_b32_e32 v172, v153
	v_pk_mul_f32 v[112:113], v[132:133], v[172:173]
	v_add_f32_e32 v113, v113, v121
	v_add_f32_e32 v117, v112, v113
	v_mul_f32_e32 v112, 0xbfb8aa3b, v117
	v_exp_f32_e32 v112, v112
	v_lshlrev_b32_e32 v152, 16, v36
	v_and_b32_e32 v176, 0xffff0000, v39
	v_add_f32_e32 v116, 1.0, v112
	v_rcp_f32_e32 v108, v118
	s_nop 0
	v_mul_f32_e32 v106, v106, v108
	v_mul_f32_e32 v118, v106, v176
	v_fma_f32 v106, v6, v173, v22
	v_pk_mul_f32 v[112:113], v[132:133], v[152:153]
	v_add_f32_e32 v106, v113, v106
	v_add_f32_e32 v172, v112, v106
	v_mul_f32_e32 v106, 0xbfb8aa3b, v172
	v_exp_f32_e32 v106, v106
	s_nop 0
	v_add_f32_e32 v120, 1.0, v106
	v_lshlrev_b32_e32 v185, 16, v32
	v_rcp_f32_e32 v106, v116
	s_nop 0
	v_mul_f32_e32 v106, v117, v106
	v_mul_f32_e32 v108, v106, v185
	v_and_b32_e32 v149, 0xffff0000, v28
	v_mov_b32_e32 v106, v149
	v_pk_mul_f32 v[112:113], v[14:15], v[106:107]
	v_lshlrev_b32_e32 v194, 16, v40
	v_add_f32_e32 v106, v113, v189
	v_add_f32_e32 v112, v112, v106
	v_mul_f32_e32 v106, 0xbfb8aa3b, v112
	v_exp_f32_e32 v106, v106
	v_and_b32_e32 v148, 0xffff0000, v36
	v_add_f32_e32 v116, 1.0, v106
	v_rcp_f32_e32 v113, v120
	s_nop 0
	v_mul_f32_e32 v106, v172, v113
	v_mul_f32_e32 v120, v106, v194
	v_fma_f32 v113, v7, v107, v23
	v_pk_mul_f32 v[106:107], v[14:15], v[148:149]
	v_and_b32_e32 v186, 0xffff0000, v32
	v_add_f32_e32 v107, v107, v113
	v_add_f32_e32 v113, v106, v107
	v_mul_f32_e32 v106, 0xbfb8aa3b, v113
	v_exp_f32_e32 v106, v106
	v_lshlrev_b32_e32 v145, 16, v29
	v_add_f32_e32 v117, 1.0, v106
	v_rcp_f32_e32 v107, v116
	s_nop 0
	v_mul_f32_e32 v106, v112, v107
	v_mul_f32_e32 v106, v106, v186
	v_cvt_pk_bf16_f32 v112, v108, v106
	v_mov_b32_e32 v168, v145
	v_pk_mul_f32 v[106:107], v[130:131], v[168:169]
	v_and_b32_e32 v195, 0xffff0000, v40
	v_add_f32_e32 v107, v107, v190
	v_add_f32_e32 v168, v106, v107
	v_mul_f32_e32 v106, 0xbfb8aa3b, v168
	v_exp_f32_e32 v106, v106
	v_lshlrev_b32_e32 v144, 16, v37
	v_add_f32_e32 v108, 1.0, v106
	v_rcp_f32_e32 v107, v117
	s_nop 0
	v_mul_f32_e32 v106, v113, v107
	v_mul_f32_e32 v117, v106, v195
	v_fma_f32 v113, v8, v169, v24
	v_pk_mul_f32 v[106:107], v[130:131], v[144:145]
	v_add_f32_e32 v107, v107, v113
	v_add_f32_e32 v113, v106, v107
	v_mul_f32_e32 v106, 0xbfb8aa3b, v113
	v_exp_f32_e32 v106, v106
	s_nop 0
	v_add_f32_e32 v116, 1.0, v106
	v_lshlrev_b32_e32 v187, 16, v33
	v_rcp_f32_e32 v106, v108
	s_nop 0
	v_mul_f32_e32 v106, v168, v106
	v_mul_f32_e32 v121, v106, v187
	v_and_b32_e32 v141, 0xffff0000, v29
	v_mov_b32_e32 v108, v141
	v_pk_mul_f32 v[106:107], v[16:17], v[108:109]
	v_lshlrev_b32_e32 v198, 16, v41
	v_add_f32_e32 v107, v107, v191
	v_add_f32_e32 v108, v106, v107
	v_mul_f32_e32 v106, 0xbfb8aa3b, v108
	v_exp_f32_e32 v106, v106
	v_rcp_f32_e32 v107, v116
	s_nop 0
	v_mul_f32_e32 v107, v113, v107
	v_add_f32_e32 v168, 1.0, v106
	v_mul_f32_e32 v116, v107, v198
	v_and_b32_e32 v140, 0xffff0000, v37
	v_fma_f32 v109, v9, v109, v25
	v_pk_mul_f32 v[106:107], v[16:17], v[140:141]
	v_and_b32_e32 v188, 0xffff0000, v33
	v_add_f32_e32 v107, v107, v109
	v_add_f32_e32 v106, v106, v107
	v_mul_f32_e32 v107, 0xbfb8aa3b, v106
	v_exp_f32_e32 v107, v107
	v_rcp_f32_e32 v109, v168
	s_nop 0
	v_mul_f32_e32 v108, v108, v109
	v_mul_f32_e32 v108, v108, v188
	v_add_f32_e32 v107, 1.0, v107
	v_cvt_pk_bf16_f32 v113, v121, v108
	global_store_dwordx4 v[114:115], v[110:113], off
	v_and_b32_e32 v199, 0xffff0000, v41
	v_rcp_f32_e32 v108, v107
	s_nop 0
	v_mul_f32_e32 v106, v106, v108
	v_add_u32_e32 v110, 0x4001, v181
	v_mul_f32_e32 v109, v106, v199
	v_cvt_pk_bf16_f32 v106, v177, v192
	v_mad_i64_i32 v[110:111], s[0:1], v110, s25, v[126:127]
	s_waitcnt vmcnt(8)
	v_lshlrev_b32_e32 v167, 16, v42
	s_waitcnt vmcnt(6)
	v_lshlrev_b32_e32 v166, 16, v50
	v_cvt_pk_bf16_f32 v107, v119, v118
	v_cvt_pk_bf16_f32 v108, v120, v117
	v_cvt_pk_bf16_f32 v109, v116, v109
	global_store_dwordx4 v[110:111], v[106:109], off
	v_fma_f32 v118, v2, v171, v18
	s_waitcnt vmcnt(6)
	v_and_b32_e32 v171, 0xffff0000, v54
	v_add_u32_e32 v106, 0x4002, v181
	v_mad_i64_i32 v[110:111], s[0:1], v106, s25, v[126:127]
	v_pk_mov_b32 v[106:107], v[166:167], v[170:171] op_sel:[1,0]
	v_fma_f32 v170, v2, v170, v18
	v_pk_mul_f32 v[106:107], v[136:137], v[106:107]
	v_lshlrev_b32_e32 v108, 16, v46
	v_add_f32_e32 v107, v107, v118
	v_add_f32_e32 v118, v106, v107
	v_mul_f32_e32 v106, 0xbfb8aa3b, v118
	v_exp_f32_e32 v106, v106
	v_and_b32_e32 v163, 0xffff0000, v42
	v_and_b32_e32 v162, 0xffff0000, v50
	v_fma_f32 v119, v3, v165, v19
	v_add_f32_e32 v176, 1.0, v106
	v_lshlrev_b32_e32 v169, 16, v54
	v_pk_mul_f32 v[106:107], v[136:137], v[166:167]
	v_add_f32_e32 v107, v107, v170
	v_add_f32_e32 v166, v106, v107
	v_mul_f32_e32 v106, 0xbfb8aa3b, v166
	v_exp_f32_e32 v106, v106
	s_nop 0
	v_add_f32_e32 v167, 1.0, v106
	v_rcp_f32_e32 v106, v176
	s_nop 0
	v_mul_f32_e32 v106, v118, v106
	v_mul_f32_e32 v108, v106, v108
	v_pk_mov_b32 v[106:107], v[162:163], v[164:165] op_sel:[1,0]
	v_fma_f32 v164, v3, v164, v19
	v_pk_mul_f32 v[106:107], v[10:11], v[106:107]
	v_and_b32_e32 v109, 0xffff0000, v46
	v_add_f32_e32 v107, v107, v119
	v_add_f32_e32 v119, v106, v107
	v_mul_f32_e32 v106, 0xbfb8aa3b, v119
	v_exp_f32_e32 v106, v106
	v_lshlrev_b32_e32 v159, 16, v43
	v_add_f32_e32 v118, 1.0, v106
	v_rcp_f32_e32 v107, v167
	s_nop 0
	v_mul_f32_e32 v106, v166, v107
	v_mul_f32_e32 v166, v106, v169
	v_pk_mul_f32 v[106:107], v[10:11], v[162:163]
	v_add_f32_e32 v107, v107, v164
	v_add_f32_e32 v107, v106, v107
	v_mul_f32_e32 v106, 0xbfb8aa3b, v107
	v_exp_f32_e32 v106, v106
	v_lshlrev_b32_e32 v158, 16, v51
	v_fma_f32 v120, v4, v161, v20
	v_add_f32_e32 v163, 1.0, v106
	v_rcp_f32_e32 v162, v118
	s_nop 0
	v_mul_f32_e32 v106, v119, v162
	v_mul_f32_e32 v106, v106, v109
	v_cvt_pk_bf16_f32 v106, v108, v106
	v_fma_f32 v161, v7, v149, v23
	v_pk_mov_b32 v[108:109], v[158:159], v[160:161] op_sel:[1,0]
	v_lshlrev_b32_e32 v112, 16, v47
	v_pk_mul_f32 v[108:109], v[134:135], v[108:109]
	v_and_b32_e32 v155, 0xffff0000, v43
	v_add_f32_e32 v109, v109, v120
	v_add_f32_e32 v120, v108, v109
	v_mul_f32_e32 v108, 0xbfb8aa3b, v120
	v_exp_f32_e32 v108, v108
	v_rcp_f32_e32 v109, v163
	s_nop 0
	v_mul_f32_e32 v107, v107, v109
	v_add_f32_e32 v118, 1.0, v108
	v_mul_f32_e32 v163, v107, v171
	v_fma_f32 v107, v4, v160, v20
	v_pk_mul_f32 v[108:109], v[134:135], v[158:159]
	v_add_f32_e32 v107, v109, v107
	v_add_f32_e32 v107, v108, v107
	v_mul_f32_e32 v108, 0xbfb8aa3b, v107
	v_exp_f32_e32 v108, v108
	s_nop 0
	v_add_f32_e32 v119, 1.0, v108
	v_rcp_f32_e32 v108, v118
	s_nop 0
	v_mul_f32_e32 v108, v120, v108
	v_mul_f32_e32 v112, v108, v112
	v_and_b32_e32 v154, 0xffff0000, v51
	v_pk_mov_b32 v[108:109], v[154:155], v[156:157] op_sel:[1,0]
	v_fma_f32 v121, v5, v157, v21
	v_pk_mul_f32 v[108:109], v[12:13], v[108:109]
	v_lshlrev_b32_e32 v172, 16, v55
	v_add_f32_e32 v109, v109, v121
	v_add_f32_e32 v121, v108, v109
	v_mul_f32_e32 v108, 0xbfb8aa3b, v121
	v_exp_f32_e32 v108, v108
	v_rcp_f32_e32 v109, v119
	s_nop 0
	v_mul_f32_e32 v107, v107, v109
	v_add_f32_e32 v118, 1.0, v108
	v_mul_f32_e32 v119, v107, v172
	v_fma_f32 v107, v5, v156, v21
	v_pk_mul_f32 v[108:109], v[12:13], v[154:155]
	v_and_b32_e32 v113, 0xffff0000, v47
	v_add_f32_e32 v107, v109, v107
	v_add_f32_e32 v154, v108, v107
	v_mul_f32_e32 v107, 0xbfb8aa3b, v154
	v_exp_f32_e32 v107, v107
	v_lshlrev_b32_e32 v151, 16, v44
	v_add_f32_e32 v120, 1.0, v107
	v_rcp_f32_e32 v108, v118
	s_nop 0
	v_mul_f32_e32 v107, v121, v108
	v_mul_f32_e32 v107, v107, v113
	v_cvt_pk_bf16_f32 v107, v112, v107
	v_lshlrev_b32_e32 v150, 16, v52
	v_fma_f32 v153, v6, v153, v22
	v_pk_mov_b32 v[108:109], v[150:151], v[152:153] op_sel:[1,0]
	v_and_b32_e32 v173, 0xffff0000, v55
	v_pk_mul_f32 v[108:109], v[132:133], v[108:109]
	v_fma_f32 v152, v6, v152, v22
	v_add_f32_e32 v109, v109, v153
	v_add_f32_e32 v118, v108, v109
	v_mul_f32_e32 v108, 0xbfb8aa3b, v118
	v_exp_f32_e32 v108, v108
	v_lshlrev_b32_e32 v114, 16, v48
	v_add_f32_e32 v112, 1.0, v108
	v_rcp_f32_e32 v109, v120
	s_nop 0
	v_mul_f32_e32 v108, v154, v109
	v_mul_f32_e32 v120, v108, v173
	v_pk_mul_f32 v[108:109], v[132:133], v[150:151]
	v_add_f32_e32 v109, v109, v152
	v_add_f32_e32 v150, v108, v109
	v_mul_f32_e32 v108, 0xbfb8aa3b, v150
	v_exp_f32_e32 v108, v108
	s_nop 0
	v_add_f32_e32 v113, 1.0, v108
	v_rcp_f32_e32 v108, v112
	s_nop 0
	v_mul_f32_e32 v108, v118, v108
	v_mul_f32_e32 v112, v108, v114
	v_and_b32_e32 v147, 0xffff0000, v44
	v_and_b32_e32 v146, 0xffff0000, v52
	v_pk_mov_b32 v[108:109], v[146:147], v[148:149] op_sel:[1,0]
	v_lshlrev_b32_e32 v174, 16, v56
	v_pk_mul_f32 v[108:109], v[14:15], v[108:109]
	v_and_b32_e32 v115, 0xffff0000, v48
	v_add_f32_e32 v109, v109, v161
	v_add_f32_e32 v121, v108, v109
	v_mul_f32_e32 v108, 0xbfb8aa3b, v121
	v_exp_f32_e32 v108, v108
	v_lshlrev_b32_e32 v143, 16, v45
	v_add_f32_e32 v114, 1.0, v108
	v_rcp_f32_e32 v109, v113
	s_nop 0
	v_mul_f32_e32 v108, v150, v109
	v_mul_f32_e32 v150, v108, v174
	v_fma_f32 v113, v7, v148, v23
	v_pk_mul_f32 v[108:109], v[14:15], v[146:147]
	v_lshlrev_b32_e32 v142, 16, v53
	v_add_f32_e32 v109, v109, v113
	v_add_f32_e32 v109, v108, v109
	v_mul_f32_e32 v108, 0xbfb8aa3b, v109
	v_exp_f32_e32 v108, v108
	v_fma_f32 v145, v8, v145, v24
	v_add_f32_e32 v118, 1.0, v108
	v_rcp_f32_e32 v113, v114
	s_nop 0
	v_mul_f32_e32 v108, v121, v113
	v_mul_f32_e32 v108, v108, v115
	v_cvt_pk_bf16_f32 v108, v112, v108
	v_pk_mov_b32 v[112:113], v[142:143], v[144:145] op_sel:[1,0]
	v_and_b32_e32 v175, 0xffff0000, v56
	v_pk_mul_f32 v[112:113], v[130:131], v[112:113]
	v_lshlrev_b32_e32 v116, 16, v49
	v_add_f32_e32 v113, v113, v145
	v_add_f32_e32 v121, v112, v113
	v_mul_f32_e32 v112, 0xbfb8aa3b, v121
	v_exp_f32_e32 v112, v112
	v_rcp_f32_e32 v113, v118
	s_nop 0
	v_mul_f32_e32 v109, v109, v113
	v_add_f32_e32 v114, 1.0, v112
	v_mul_f32_e32 v118, v109, v175
	v_fma_f32 v109, v8, v144, v24
	v_pk_mul_f32 v[112:113], v[130:131], v[142:143]
	v_add_f32_e32 v109, v113, v109
	v_add_f32_e32 v109, v112, v109
	v_mul_f32_e32 v112, 0xbfb8aa3b, v109
	v_exp_f32_e32 v112, v112
	s_nop 0
	v_add_f32_e32 v115, 1.0, v112
	v_rcp_f32_e32 v112, v114
	s_nop 0
	v_mul_f32_e32 v112, v121, v112
	v_mul_f32_e32 v114, v112, v116
	v_and_b32_e32 v139, 0xffff0000, v45
	v_and_b32_e32 v138, 0xffff0000, v53
	v_pk_mov_b32 v[112:113], v[138:139], v[140:141] op_sel:[1,0]
	v_fma_f32 v168, v9, v141, v25
	v_pk_mul_f32 v[112:113], v[16:17], v[112:113]
	v_lshlrev_b32_e32 v186, 16, v57
	v_add_f32_e32 v113, v113, v168
	v_add_f32_e32 v141, v112, v113
	v_mul_f32_e32 v112, 0xbfb8aa3b, v141
	v_exp_f32_e32 v112, v112
	v_rcp_f32_e32 v113, v115
	s_nop 0
	v_mul_f32_e32 v109, v109, v113
	v_add_f32_e32 v116, 1.0, v112
	v_mul_f32_e32 v115, v109, v186
	v_fma_f32 v109, v9, v140, v25
	v_and_b32_e32 v117, 0xffff0000, v49
	v_pk_mul_f32 v[112:113], v[16:17], v[138:139]
	v_and_b32_e32 v187, 0xffff0000, v57
	v_add_f32_e32 v109, v113, v109
	v_add_f32_e32 v112, v112, v109
	v_mul_f32_e32 v109, 0xbfb8aa3b, v112
	v_exp_f32_e32 v109, v109
	v_rcp_f32_e32 v113, v116
	s_nop 0
	v_mul_f32_e32 v113, v141, v113
	s_mov_b64 s[16:17], -1
	v_add_f32_e32 v116, 1.0, v109
	v_mul_f32_e32 v109, v113, v117
	v_cvt_pk_bf16_f32 v109, v114, v109
	global_store_dwordx4 v[110:111], v[106:109], off
	v_add_u32_e32 v110, 0x4003, v181
	v_mad_i64_i32 v[110:111], s[0:1], v110, s25, v[126:127]
	v_rcp_f32_e32 v106, v116
	s_nop 0
	v_mul_f32_e32 v106, v112, v106
	v_mul_f32_e32 v109, v106, v187
	v_cvt_pk_bf16_f32 v106, v166, v163
	v_cvt_pk_bf16_f32 v107, v119, v120
	v_cvt_pk_bf16_f32 v108, v150, v118
	v_cvt_pk_bf16_f32 v109, v115, v109
	global_store_dwordx4 v[110:111], v[106:109], off
	s_and_saveexec_b64 s[6:7], s[4:5]
	s_cbranch_execz .LBB0_2212
	v_add_u32_e32 v107, s21, v182
	v_cmp_gt_i32_e32 vcc, s23, v107
	s_and_saveexec_b64 s[4:5], vcc
	s_cbranch_execz .LBB0_2226
	v_add_u32_e32 v106, s20, v181
	v_add_u32_e32 v62, 0x4000, v106
	v_mov_b64_e32 v[50:51], s[12:13]
	v_mad_i64_i32 v[26:27], s[0:1], v62, s18, v[50:51]
	v_lshl_add_u64 v[34:35], v[26:27], 0, v[122:123]
	v_add_co_u32_e32 v36, vcc, 0x1000, v34
	v_mov_b32_e32 v65, 0
	s_nop 0
	v_addc_co_u32_e32 v37, vcc, 0, v35, vcc
	global_load_dwordx4 v[26:29], v[34:35], off
	global_load_dwordx4 v[30:33], v[36:37], off offset:1536
	v_add_u32_e32 v34, 0x4001, v106
	v_mad_i64_i32 v[34:35], s[0:1], v34, s18, v[50:51]
	v_lshl_add_u64 v[42:43], v[34:35], 0, v[122:123]
	v_add_co_u32_e32 v44, vcc, 0x1000, v42
	v_mov_b32_e32 v64, 0
	s_nop 0
	v_addc_co_u32_e32 v45, vcc, 0, v43, vcc
	global_load_dwordx4 v[34:37], v[42:43], off
	global_load_dwordx4 v[38:41], v[44:45], off offset:1536
	v_add_u32_e32 v42, 0x4002, v106
	v_mad_i64_i32 v[42:43], s[0:1], v42, s18, v[50:51]
	v_lshl_add_u64 v[52:53], v[42:43], 0, v[122:123]
	v_add_co_u32_e32 v54, vcc, 0x1000, v52
	v_mov_b32_e32 v63, 0
	s_nop 0
	v_addc_co_u32_e32 v55, vcc, 0, v53, vcc
	global_load_dwordx4 v[42:45], v[52:53], off
	global_load_dwordx4 v[46:49], v[54:55], off offset:1536
	v_add_u32_e32 v52, 0x4003, v106
	v_mad_i64_i32 v[50:51], s[0:1], v52, s18, v[50:51]
	v_lshl_add_u64 v[58:59], v[50:51], 0, v[122:123]
	v_add_co_u32_e32 v60, vcc, 0x1000, v58
	s_nop 1
	v_addc_co_u32_e32 v61, vcc, 0, v59, vcc
	global_load_dwordx4 v[50:53], v[58:59], off
	global_load_dwordx4 v[54:57], v[60:61], off offset:1536
	v_cmp_lt_i32_e32 vcc, s24, v107
	v_mov_b32_e32 v61, 0
	v_mov_b32_e32 v60, 0
	v_cndmask_b32_e64 v58, v180, 4, vcc
	v_and_b32_e32 v58, v58, v62
	v_cmp_ne_u32_e32 vcc, 0, v58
	v_mov_b32_e32 v59, 0
	v_mov_b32_e32 v58, 0
	v_mov_b32_e32 v62, 0
	s_and_saveexec_b64 s[16:17], vcc
	s_cbranch_execz .LBB0_2225
	v_add_u32_e32 v58, 0x3ffe, v106
	v_add_u32_e32 v60, 0x3fff, v106
	v_mad_i64_i32 v[58:59], s[0:1], v58, s18, v[124:125]
	s_nop 1
	v_mad_i64_i32 v[60:61], s[0:1], v60, s18, v[124:125]
	global_load_dwordx4 v[62:65], v[58:59], off
	s_nop 0
	global_load_dwordx4 v[58:61], v[60:61], off
